# scan: 2-byte LDS reads of the conv output issued as early as their destination register allows (pure instruction motion)
# baseline (speedup 1.0000x reference)
; __device__ __forceinline__ float bf2f(bf16_t b) { return __uint_as_float(((unsigned)b) << 16); }
; __device__ __forceinline__ float fast_sigmoid(float x) { return __builtin_amdgcn_rcpf(1.0f + __builtin_amdgcn_exp2f(-1.4426950408889634f * x)); }
; template <int DIR>
; __device__ __forceinline__ void scan_dir(PP p, const bf16_t* xs, const ScanW& w, ScanW& wn, int ndir, int nct, bool do_next, int n, int ct, int l31, int hl, int id, int rowbase, bool latent, float (&hf)[2][16]) {
;     ...
;     for (int rt = 0; rt < 2; ++rt) {
;         bf16x8 af[4];
; #pragma unroll
;         for (int st = 0; st < 4; ++st) af[st] = *(const bf16x8*)(xs + (32 * rt + l31) * XS + 64 * n + 16 * st + 8 * hl);
;         f32x16 ga, gi;
; #pragma unroll
;         for (int i = 0; i < 16; ++i) { ga[i] = 0.f; gi[i] = 0.f; }
; #pragma unroll
;         for (int st = 0; st < 4; ++st) { ga = __builtin_amdgcn_mfma_f32_32x32x16_bf16(af[st], wfa[st], ga, 0, 0, 0); gi = __builtin_amdgcn_mfma_f32_32x32x16_bf16(af[st], wfi[st], gi, 0, 0, 0); }
; #pragma unroll
;         for (int i = 0; i < 16; ++i) {
;             const int token = 32 * rt + 8 * (i >> 2) + 4 * hl + (i & 3);
;             const float xv = bf2f(xs[token * XS + ch]);
;             const float rr = fast_sigmoid(ga[i] + ba), ii = fast_sigmoid(gi[i] + bi);
;             const float la2 = rr * sp8l2;
;             const float av = __builtin_amdgcn_exp2f(la2);
;             const float t2 = la2 * 1.3862943611f;
;             float em1p = t2 * (1.0f + t2 * (0.5f + t2 * (0.16666667f + t2 * (0.041666668f + t2 * 0.0083333333f)))), em1e = __builtin_fmaf(av, av, -1.0f);
;             asm volatile("" : "+v"(em1p), "+v"(em1e));
;             const float em1 = (t2 > -0.1f) ? em1p : em1e;
;             a[rt][i] = av; u[rt][i] = __builtin_amdgcn_sqrtf(-em1) * (ii * xv);
;         }
.LBB0_378:
	ds_read_b128 v[2:5], v187
	s_lshl_b32 s48, s80, 5
	v_or_b32_e32 v66, s48, v150
	v_lshl_add_u32 v42, v66, 1, 0
	v_add_u32_e32 v0, v42, v151
	ds_read_u16 v43, v0
	ds_read_b128 v[34:37], v187 offset:32
	ds_read_b128 v[38:41], v187 offset:64
	s_waitcnt vmcnt(7) lgkmcnt(3)
	v_mfma_f32_32x32x16_bf16 v[18:33], v[2:5], v[114:117], 0
	s_waitcnt vmcnt(2)
	v_mfma_f32_32x32x16_bf16 v[2:17], v[2:5], v[134:137], 0
	s_waitcnt lgkmcnt(1)
	v_mfma_f32_32x32x16_bf16 v[18:33], v[34:37], v[118:121], v[18:33]
	v_mfma_f32_32x32x16_bf16 v[2:17], v[34:37], v[126:129], v[2:17]
	ds_read_b128 v[34:37], v187 offset:96
	s_waitcnt lgkmcnt(1)
	v_mfma_f32_32x32x16_bf16 v[18:33], v[38:41], v[122:125], v[18:33]
	s_waitcnt vmcnt(1) lgkmcnt(0)
	v_mfma_f32_32x32x16_bf16 v[18:33], v[34:37], v[138:141], v[18:33]
	v_mfma_f32_32x32x16_bf16 v[2:17], v[38:41], v[130:133], v[2:17]
	s_nop 10
	v_add_f32_e32 v18, v192, v18
	v_mul_f32_e32 v18, 0xbfb8aa3b, v18
	v_exp_f32_e32 v18, v18
	v_add_f32_e32 v19, v192, v19
	v_mul_f32_e32 v19, 0xbfb8aa3b, v19
	v_exp_f32_e32 v19, v19
	v_add_f32_e32 v18, 1.0, v18
	s_waitcnt vmcnt(0)
	v_mfma_f32_32x32x16_bf16 v[2:17], v[34:37], v[142:145], v[2:17]
	v_rcp_f32_e32 v18, v18
	v_add_f32_e32 v19, 1.0, v19
	v_rcp_f32_e32 v19, v19
	v_lshlrev_b32_e32 v34, 16, v43
	v_mul_f32_e32 v18, v194, v18
	v_exp_f32_e32 v50, v18
	v_mul_f32_e32 v18, 0x3fb17218, v18
	s_nop 4
	v_add_f32_e32 v2, v191, v2
	v_mul_f32_e32 v2, 0xbfb8aa3b, v2
	v_exp_f32_e32 v2, v2
	v_fmamk_f32 v35, v18, 0x3c088888, v186
	v_fmaak_f32 v35, v18, v35, 0x3e2aaaab
	v_fma_f32 v35, v18, v35, 0.5
	v_add_f32_e32 v2, 1.0, v2
	v_add_f32_e32 v3, v191, v3
	v_rcp_f32_e32 v2, v2
	v_fma_f32 v35, v18, v35, 1.0
	v_mul_f32_e32 v3, 0xbfb8aa3b, v3
	v_mul_f32_e32 v35, v18, v35
	v_fma_f32 v36, v50, v50, -1.0
	v_exp_f32_e32 v3, v3
	v_mul_f32_e32 v19, v194, v19
	v_cmp_lt_f32_e32 vcc, s76, v18
	v_exp_f32_e32 v52, v19
	v_mul_f32_e32 v19, 0x3fb17218, v19
	v_cndmask_b32_e32 v18, v36, v35, vcc
	v_fmamk_f32 v35, v19, 0x3c088888, v186
	v_mul_f32_e32 v2, v2, v34
	ds_read_u16 v34, v0 offset:1040
	v_fmaak_f32 v35, v19, v35, 0x3e2aaaab
	v_sqrt_f32_e64 v18, -v18
	v_add_f32_e32 v3, 1.0, v3
	v_fma_f32 v35, v19, v35, 0.5
	v_add_f32_e32 v4, v191, v4
	v_rcp_f32_e32 v3, v3
	v_fma_f32 v35, v19, v35, 1.0
	v_mul_f32_e32 v4, 0xbfb8aa3b, v4
	v_mul_f32_e32 v35, v19, v35
	v_fma_f32 v36, v52, v52, -1.0
	v_cmp_lt_f32_e32 vcc, s76, v19
	v_exp_f32_e32 v4, v4
	v_mul_f32_e32 v2, v2, v18
	v_cndmask_b32_e32 v19, v36, v35, vcc
	v_sqrt_f32_e64 v19, -v19
	s_waitcnt lgkmcnt(0)
	v_lshlrev_b32_e32 v18, 16, v34
	v_mul_f32_e32 v3, v3, v18
	ds_read_u16 v18, v0 offset:2080
	v_add_f32_e32 v4, 1.0, v4
	v_rcp_f32_e32 v4, v4
	v_mul_f32_e32 v3, v3, v19
	v_add_f32_e32 v19, v192, v20
	v_mul_f32_e32 v19, 0xbfb8aa3b, v19
	v_exp_f32_e32 v19, v19
	s_waitcnt lgkmcnt(0)
	v_lshlrev_b32_e32 v18, 16, v18
	v_mul_f32_e32 v4, v4, v18
	v_add_f32_e32 v18, v192, v21
	v_mul_f32_e32 v18, 0xbfb8aa3b, v18
	v_exp_f32_e32 v18, v18
	v_add_f32_e32 v19, 1.0, v19
	v_rcp_f32_e32 v19, v19
	v_add_f32_e32 v5, v191, v5
	v_add_f32_e32 v18, 1.0, v18
	v_rcp_f32_e32 v18, v18
	v_mul_f32_e32 v19, v194, v19
	v_exp_f32_e32 v51, v19
	v_mul_f32_e32 v19, 0x3fb17218, v19
	v_fmamk_f32 v20, v19, 0x3c088888, v186
	v_fmaak_f32 v20, v19, v20, 0x3e2aaaab
	v_mul_f32_e32 v18, v194, v18
	v_fma_f32 v20, v19, v20, 0.5
	v_mul_f32_e32 v5, 0xbfb8aa3b, v5
	v_exp_f32_e32 v54, v18
	v_mul_f32_e32 v18, 0x3fb17218, v18
	v_fma_f32 v20, v19, v20, 1.0
	v_exp_f32_e32 v5, v5
	v_fmamk_f32 v21, v18, 0x3c088888, v186
	v_mul_f32_e32 v20, v19, v20
	v_fma_f32 v34, v51, v51, -1.0
	v_fmaak_f32 v21, v18, v21, 0x3e2aaaab
	v_cmp_lt_f32_e32 vcc, s76, v19
	v_fma_f32 v21, v18, v21, 0.5
	v_fma_f32 v21, v18, v21, 1.0
	v_cndmask_b32_e32 v19, v34, v20, vcc
	ds_read_u16 v20, v0 offset:3120
	v_sqrt_f32_e64 v19, -v19
	v_add_f32_e32 v5, 1.0, v5
	v_mul_f32_e32 v21, v18, v21
	v_fma_f32 v34, v54, v54, -1.0
	v_cmp_lt_f32_e32 vcc, s76, v18
	v_rcp_f32_e32 v5, v5
	v_add_f32_e32 v6, v191, v6
	v_cndmask_b32_e32 v18, v34, v21, vcc
	v_sqrt_f32_e64 v18, -v18
	v_mul_f32_e32 v6, 0xbfb8aa3b, v6
	v_mul_f32_e32 v4, v4, v19
	s_waitcnt lgkmcnt(0)
	v_lshlrev_b32_e32 v19, 16, v20
	v_exp_f32_e32 v6, v6
	v_mul_f32_e32 v5, v5, v19
	v_mul_f32_e32 v5, v18, v5
	v_add_u32_e32 v18, v42, v152
	ds_read_u16 v19, v18
	v_add_f32_e32 v20, v192, v22
	v_mul_f32_e32 v20, 0xbfb8aa3b, v20
	v_add_f32_e32 v6, 1.0, v6
	v_exp_f32_e32 v20, v20
	v_rcp_f32_e32 v6, v6
	s_waitcnt lgkmcnt(0)
	v_lshlrev_b32_e32 v19, 16, v19
	v_add_f32_e32 v7, v191, v7
	v_add_f32_e32 v20, 1.0, v20
	v_mul_f32_e32 v6, v6, v19
	v_add_f32_e32 v19, v192, v23
	v_rcp_f32_e32 v20, v20
	v_mul_f32_e32 v19, 0xbfb8aa3b, v19
	v_exp_f32_e32 v19, v19
	v_mul_f32_e32 v7, 0xbfb8aa3b, v7
	v_mul_f32_e32 v20, v194, v20
	v_exp_f32_e32 v53, v20
	v_mul_f32_e32 v20, 0x3fb17218, v20
	v_add_f32_e32 v19, 1.0, v19
	v_fmamk_f32 v21, v20, 0x3c088888, v186
	v_rcp_f32_e32 v19, v19
	v_fmaak_f32 v21, v20, v21, 0x3e2aaaab
	v_fma_f32 v21, v20, v21, 0.5
	v_fma_f32 v21, v20, v21, 1.0
	v_mul_f32_e32 v21, v20, v21
	v_fma_f32 v22, v53, v53, -1.0
	v_mul_f32_e32 v19, v194, v19
	v_cmp_lt_f32_e32 vcc, s76, v20
	v_exp_f32_e32 v55, v19
	v_mul_f32_e32 v19, 0x3fb17218, v19
	v_cndmask_b32_e32 v20, v22, v21, vcc
	ds_read_u16 v21, v0 offset:9360
	v_exp_f32_e32 v7, v7
	v_fmamk_f32 v22, v19, 0x3c088888, v186
	v_fmaak_f32 v22, v19, v22, 0x3e2aaaab
	v_fma_f32 v22, v19, v22, 0.5
	v_fma_f32 v22, v19, v22, 1.0
	v_sqrt_f32_e64 v20, -v20
	v_add_f32_e32 v7, 1.0, v7
	v_mul_f32_e32 v22, v19, v22
	v_fma_f32 v23, v55, v55, -1.0
	v_cmp_lt_f32_e32 vcc, s76, v19
	v_rcp_f32_e32 v7, v7
	v_add_f32_e32 v8, v191, v8
	v_cndmask_b32_e32 v19, v23, v22, vcc
	v_sqrt_f32_e64 v19, -v19
	v_mul_f32_e32 v8, 0xbfb8aa3b, v8
	v_exp_f32_e32 v8, v8
	v_mul_f32_e32 v6, v20, v6
	s_waitcnt lgkmcnt(0)
; __device__ __forceinline__ float bf2f(bf16_t b) { return __uint_as_float(((unsigned)b) << 16); }
; __device__ __forceinline__ float fast_sigmoid(float x) { return __builtin_amdgcn_rcpf(1.0f + __builtin_amdgcn_exp2f(-1.4426950408889634f * x)); }
; template <int DIR>
; __device__ __forceinline__ void scan_dir(PP p, const bf16_t* xs, const ScanW& w, ScanW& wn, int ndir, int nct, bool do_next, int n, int ct, int l31, int hl, int id, int rowbase, bool latent, float (&hf)[2][16]) {
;     ...
;         for (int i = 0; i < 16; ++i) {
;             const int token = 32 * rt + 8 * (i >> 2) + 4 * hl + (i & 3);
;             const float xv = bf2f(xs[token * XS + ch]);
;             const float rr = fast_sigmoid(ga[i] + ba), ii = fast_sigmoid(gi[i] + bi);
;             const float la2 = rr * sp8l2;
;             const float av = __builtin_amdgcn_exp2f(la2);
;             const float t2 = la2 * 1.3862943611f;
;             float em1p = t2 * (1.0f + t2 * (0.5f + t2 * (0.16666667f + t2 * (0.041666668f + t2 * 0.0083333333f)))), em1e = __builtin_fmaf(av, av, -1.0f);
;             asm volatile("" : "+v"(em1p), "+v"(em1e));
;             const float em1 = (t2 > -0.1f) ? em1p : em1e;
;             a[rt][i] = av; u[rt][i] = __builtin_amdgcn_sqrtf(-em1) * (ii * xv);
;         }
	v_lshlrev_b32_e32 v20, 16, v21
	v_mul_f32_e32 v7, v7, v20
	v_mul_f32_e32 v7, v19, v7
	ds_read_u16 v19, v0 offset:10400
	v_add_f32_e32 v20, v192, v24
	v_mul_f32_e32 v20, 0xbfb8aa3b, v20
	v_add_f32_e32 v8, 1.0, v8
	v_exp_f32_e32 v20, v20
	v_rcp_f32_e32 v8, v8
	s_waitcnt lgkmcnt(0)
	v_lshlrev_b32_e32 v19, 16, v19
	v_add_f32_e32 v9, v191, v9
	v_add_f32_e32 v20, 1.0, v20
	v_mul_f32_e32 v8, v8, v19
	v_add_f32_e32 v19, v192, v25
	v_rcp_f32_e32 v20, v20
	v_mul_f32_e32 v19, 0xbfb8aa3b, v19
	v_exp_f32_e32 v19, v19
	v_mul_f32_e32 v9, 0xbfb8aa3b, v9
	v_mul_f32_e32 v20, v194, v20
	v_exp_f32_e32 v67, v20
	v_mul_f32_e32 v20, 0x3fb17218, v20
	v_add_f32_e32 v19, 1.0, v19
	v_fmamk_f32 v21, v20, 0x3c088888, v186
	v_rcp_f32_e32 v19, v19
	v_fmaak_f32 v21, v20, v21, 0x3e2aaaab
	v_fma_f32 v21, v20, v21, 0.5
	v_fma_f32 v21, v20, v21, 1.0
	v_mul_f32_e32 v21, v20, v21
	v_fma_f32 v22, v67, v67, -1.0
	v_mul_f32_e32 v19, v194, v19
	v_cmp_lt_f32_e32 vcc, s76, v20
	v_exp_f32_e32 v69, v19
	v_mul_f32_e32 v19, 0x3fb17218, v19
	v_cndmask_b32_e32 v20, v22, v21, vcc
	ds_read_u16 v21, v0 offset:11440
	v_exp_f32_e32 v9, v9
	v_fmamk_f32 v22, v19, 0x3c088888, v186
	v_fmaak_f32 v22, v19, v22, 0x3e2aaaab
	v_fma_f32 v22, v19, v22, 0.5
	v_fma_f32 v22, v19, v22, 1.0
	v_sqrt_f32_e64 v20, -v20
	v_add_f32_e32 v9, 1.0, v9
	v_mul_f32_e32 v22, v19, v22
	v_fma_f32 v23, v69, v69, -1.0
	v_cmp_lt_f32_e32 vcc, s76, v19
	v_rcp_f32_e32 v9, v9
	v_add_f32_e32 v10, v191, v10
	v_cndmask_b32_e32 v19, v23, v22, vcc
	v_sqrt_f32_e64 v19, -v19
	v_mul_f32_e32 v10, 0xbfb8aa3b, v10
	v_exp_f32_e32 v10, v10
	v_mul_f32_e32 v8, v20, v8
	s_waitcnt lgkmcnt(0)
	v_lshlrev_b32_e32 v20, 16, v21
	v_mul_f32_e32 v9, v9, v20
	v_mul_f32_e32 v76, v19, v9
	ds_read_u16 v9, v18 offset:8320
	v_add_f32_e32 v19, v192, v26
	v_mul_f32_e32 v19, 0xbfb8aa3b, v19
	v_add_f32_e32 v10, 1.0, v10
	v_exp_f32_e32 v19, v19
	v_rcp_f32_e32 v10, v10
	s_waitcnt lgkmcnt(0)
	v_lshlrev_b32_e32 v9, 16, v9
	v_add_f32_e32 v11, v191, v11
	v_add_f32_e32 v19, 1.0, v19
	v_mul_f32_e32 v9, v10, v9
	v_add_f32_e32 v10, v192, v27
	v_rcp_f32_e32 v19, v19
	v_mul_f32_e32 v10, 0xbfb8aa3b, v10
	v_exp_f32_e32 v10, v10
	v_mul_f32_e32 v11, 0xbfb8aa3b, v11
	v_mul_f32_e32 v19, v194, v19
	v_exp_f32_e32 v68, v19
	v_mul_f32_e32 v19, 0x3fb17218, v19
	v_add_f32_e32 v10, 1.0, v10
	v_fmamk_f32 v20, v19, 0x3c088888, v186
	v_rcp_f32_e32 v10, v10
	v_fmaak_f32 v20, v19, v20, 0x3e2aaaab
	v_fma_f32 v20, v19, v20, 0.5
	v_fma_f32 v20, v19, v20, 1.0
	v_mul_f32_e32 v20, v19, v20
	v_fma_f32 v21, v68, v68, -1.0
	v_mul_f32_e32 v10, v194, v10
	v_cmp_lt_f32_e32 vcc, s76, v19
	v_exp_f32_e32 v71, v10
	v_mul_f32_e32 v10, 0x3fb17218, v10
	v_cndmask_b32_e32 v19, v21, v20, vcc
	ds_read_u16 v20, v0 offset:17680
	v_exp_f32_e32 v11, v11
	v_fmamk_f32 v21, v10, 0x3c088888, v186
	v_fmaak_f32 v21, v10, v21, 0x3e2aaaab
	v_fma_f32 v21, v10, v21, 0.5
	v_fma_f32 v21, v10, v21, 1.0
	v_sqrt_f32_e64 v19, -v19
	v_add_f32_e32 v11, 1.0, v11
	v_mul_f32_e32 v21, v10, v21
	v_fma_f32 v22, v71, v71, -1.0
	v_cmp_lt_f32_e32 vcc, s76, v10
	v_rcp_f32_e32 v11, v11
	v_mul_f32_e32 v74, v19, v9
	v_cndmask_b32_e32 v10, v22, v21, vcc
	v_sqrt_f32_e64 v10, -v10
	s_waitcnt lgkmcnt(0)
	v_lshlrev_b32_e32 v9, 16, v20
	v_mul_f32_e32 v9, v11, v9
	v_add_f32_e32 v11, v191, v12
	v_mul_f32_e32 v73, v10, v9
	ds_read_u16 v9, v0 offset:18720
	v_add_f32_e32 v10, v192, v28
	v_mul_f32_e32 v10, 0xbfb8aa3b, v10
	v_exp_f32_e32 v10, v10
	v_mul_f32_e32 v11, 0xbfb8aa3b, v11
	v_exp_f32_e32 v11, v11
	v_add_f32_e32 v10, 1.0, v10
	v_rcp_f32_e32 v10, v10
	s_waitcnt lgkmcnt(0)
	ds_read_u16 v20, v0 offset:19760
	v_lshlrev_b32_e32 v9, 16, v9
	v_add_f32_e32 v11, 1.0, v11
	v_rcp_f32_e32 v11, v11
	v_mul_f32_e32 v10, v194, v10
	v_exp_f32_e32 v70, v10
	v_mul_f32_e32 v10, 0x3fb17218, v10
	v_fmamk_f32 v12, v10, 0x3c088888, v186
	v_fmaak_f32 v12, v10, v12, 0x3e2aaaab
	v_fma_f32 v12, v10, v12, 0.5
	v_fma_f32 v12, v10, v12, 1.0
	v_mul_f32_e32 v12, v10, v12
	v_fma_f32 v19, v70, v70, -1.0
	v_cmp_lt_f32_e32 vcc, s76, v10
	v_mul_f32_e32 v9, v11, v9
	v_add_f32_e32 v11, v191, v13
	v_cndmask_b32_e32 v10, v19, v12, vcc
	v_add_f32_e32 v12, v192, v29
	v_mul_f32_e32 v12, 0xbfb8aa3b, v12
	v_exp_f32_e32 v12, v12
	v_sqrt_f32_e64 v19, -v10
	v_mul_f32_e32 v11, 0xbfb8aa3b, v11
	v_exp_f32_e32 v21, v11
	v_add_f32_e32 v10, 1.0, v12
	v_rcp_f32_e32 v10, v10
	v_add_f32_e32 v11, v192, v30
	v_mul_f32_e32 v11, 0xbfb8aa3b, v11
	v_exp_f32_e32 v11, v11
	v_mul_f32_e32 v10, v194, v10
	v_mul_f32_e32 v22, 0x3fb17218, v10
	v_exp_f32_e32 v75, v10
	v_fmamk_f32 v10, v22, 0x3c088888, v186
	v_fmaak_f32 v10, v22, v10, 0x3e2aaaab
	v_fma_f32 v10, v22, v10, 0.5
	v_fma_f32 v10, v22, v10, 1.0
	v_mul_f32_e32 v23, v22, v10
	v_add_f32_e32 v10, 1.0, v11
	v_rcp_f32_e32 v10, v10
	v_add_f32_e32 v11, v192, v31
	v_mul_f32_e32 v11, 0xbfb8aa3b, v11
	v_exp_f32_e32 v11, v11
	v_mul_f32_e32 v10, v194, v10
	v_mul_f32_e32 v60, 0x3fb17218, v10
	v_exp_f32_e32 v72, v10
	v_fmamk_f32 v10, v60, 0x3c088888, v186
	v_fmaak_f32 v10, v60, v10, 0x3e2aaaab
	v_fma_f32 v10, v60, v10, 0.5
	v_fma_f32 v10, v60, v10, 1.0
	v_mul_f32_e32 v61, v60, v10
	v_add_f32_e32 v10, 1.0, v11
	v_rcp_f32_e32 v10, v10
	v_add_f32_e32 v11, v192, v32
	v_mul_f32_e32 v11, 0xbfb8aa3b, v11
	v_exp_f32_e32 v11, v11
	v_mul_f32_e32 v10, v194, v10
	v_mul_f32_e32 v64, 0x3fb17218, v10
	v_exp_f32_e32 v78, v10
	v_fmamk_f32 v10, v64, 0x3c088888, v186
	v_fmaak_f32 v10, v64, v10, 0x3e2aaaab
	v_fma_f32 v10, v64, v10, 0.5
	v_fma_f32 v10, v64, v10, 1.0
	v_mul_f32_e32 v65, v64, v10
	v_add_f32_e32 v10, 1.0, v11
	v_rcp_f32_e32 v10, v10
	v_add_f32_e32 v11, v192, v33
	v_mul_f32_e32 v11, 0xbfb8aa3b, v11
	v_exp_f32_e32 v11, v11
	v_mul_f32_e32 v10, v194, v10
	v_mul_f32_e32 v146, 0x3fb17218, v10
	v_exp_f32_e32 v77, v10
	v_fmamk_f32 v10, v146, 0x3c088888, v186
	v_fmaak_f32 v10, v146, v10, 0x3e2aaaab
	v_fma_f32 v10, v146, v10, 0.5
	v_fma_f32 v10, v146, v10, 1.0
	v_mul_f32_e32 v147, v146, v10
	v_add_f32_e32 v10, 1.0, v11
	v_rcp_f32_e32 v10, v10
	v_fma_f32 v24, v75, v75, -1.0
	v_mul_f32_e32 v209, v19, v9
	v_mul_f32_e32 v10, v194, v10
	v_mul_f32_e32 v156, 0x3fb17218, v10
	v_add_f32_e32 v19, 1.0, v21
	v_cmp_lt_f32_e32 vcc, s76, v22
	v_exp_f32_e32 v79, v10
	v_fmamk_f32 v10, v156, 0x3c088888, v186
	v_rcp_f32_e32 v35, v19
	v_cndmask_b32_e32 v19, v24, v23, vcc
	v_fmaak_f32 v10, v156, v10, 0x3e2aaaab
	v_sqrt_f32_e64 v36, -v19
	v_fma_f32 v10, v156, v10, 0.5
	v_fma_f32 v10, v156, v10, 1.0
	s_waitcnt lgkmcnt(0)
; __device__ __forceinline__ float bf2f(bf16_t b) { return __uint_as_float(((unsigned)b) << 16); }
; __device__ __forceinline__ float fast_sigmoid(float x) { return __builtin_amdgcn_rcpf(1.0f + __builtin_amdgcn_exp2f(-1.4426950408889634f * x)); }
; template <int DIR>
; __device__ __forceinline__ void scan_dir(PP p, const bf16_t* xs, const ScanW& w, ScanW& wn, int ndir, int nct, bool do_next, int n, int ct, int l31, int hl, int id, int rowbase, bool latent, float (&hf)[2][16]) {
;     ...
;     for (int rt = 0; rt < 2; ++rt) {
;         bf16x8 af[4];
; #pragma unroll
;         for (int st = 0; st < 4; ++st) af[st] = *(const bf16x8*)(xs + (32 * rt + l31) * XS + 64 * n + 16 * st + 8 * hl);
;         f32x16 ga, gi;
; #pragma unroll
;         for (int i = 0; i < 16; ++i) { ga[i] = 0.f; gi[i] = 0.f; }
; #pragma unroll
;         for (int st = 0; st < 4; ++st) { ga = __builtin_amdgcn_mfma_f32_32x32x16_bf16(af[st], wfa[st], ga, 0, 0, 0); gi = __builtin_amdgcn_mfma_f32_32x32x16_bf16(af[st], wfi[st], gi, 0, 0, 0); }
; #pragma unroll
;         for (int i = 0; i < 16; ++i) {
;             const int token = 32 * rt + 8 * (i >> 2) + 4 * hl + (i & 3);
;             const float xv = bf2f(xs[token * XS + ch]);
;             const float rr = fast_sigmoid(ga[i] + ba), ii = fast_sigmoid(gi[i] + bi);
;             const float la2 = rr * sp8l2;
;             const float av = __builtin_amdgcn_exp2f(la2);
;             const float t2 = la2 * 1.3862943611f;
;             float em1p = t2 * (1.0f + t2 * (0.5f + t2 * (0.16666667f + t2 * (0.041666668f + t2 * 0.0083333333f)))), em1e = __builtin_fmaf(av, av, -1.0f);
;             asm volatile("" : "+v"(em1p), "+v"(em1e));
;             const float em1 = (t2 > -0.1f) ? em1p : em1e;
;             a[rt][i] = av; u[rt][i] = __builtin_amdgcn_sqrtf(-em1) * (ii * xv);
;         }
	ds_read_u16 v34, v18 offset:16640
	ds_read_u16 v63, v0 offset:26000
	v_lshlrev_b32_e32 v9, 16, v20
	v_fma_f32 v62, v72, v72, -1.0
	v_fma_f32 v80, v78, v78, -1.0
	v_fma_f32 v154, v77, v77, -1.0
	v_mul_f32_e32 v158, v156, v10
	v_fma_f32 v159, v79, v79, -1.0
	v_mul_f32_e32 v9, v35, v9
	ds_read_u16 v81, v0 offset:27040
	ds_read_u16 v155, v0 offset:28080
	ds_read_b128 v[10:13], v187 offset:33280
	ds_read_u16 v195, v18 offset:24960
	v_mul_f32_e32 v217, v36, v9
	v_add_f32_e32 v9, v191, v14
	v_mul_f32_e32 v9, 0xbfb8aa3b, v9
	v_exp_f32_e32 v9, v9
	v_add_f32_e32 v15, v191, v15
	v_mul_f32_e32 v15, 0xbfb8aa3b, v15
	v_exp_f32_e32 v15, v15
	v_add_f32_e32 v9, 1.0, v9
	v_rcp_f32_e32 v9, v9
	ds_read_b128 v[56:59], v187 offset:33312
	s_waitcnt lgkmcnt(6)
	v_lshlrev_b32_e32 v14, 16, v34
	s_waitcnt lgkmcnt(2)
	v_mfma_f32_32x32x16_bf16 v[34:49], v[10:13], v[134:137], 0
	v_cmp_lt_f32_e32 vcc, s76, v60
	v_mul_f32_e32 v9, v9, v14
	v_add_f32_e32 v14, 1.0, v15
	v_rcp_f32_e32 v14, v14
	v_mfma_f32_32x32x16_bf16 v[18:33], v[10:13], v[114:117], 0
	v_cndmask_b32_e32 v10, v62, v61, vcc
	v_sqrt_f32_e64 v60, -v10
	ds_read_b128 v[10:13], v187 offset:33344
	v_cmp_lt_f32_e32 vcc, s76, v64
	v_mul_f32_e32 v197, v60, v9
	v_lshlrev_b32_e32 v9, 16, v63
	v_mul_f32_e32 v9, v14, v9
	v_add_f32_e32 v14, v191, v16
	s_waitcnt lgkmcnt(1)
	v_mfma_f32_32x32x16_bf16 v[34:49], v[56:59], v[126:129], v[34:49]
	v_mul_f32_e32 v14, 0xbfb8aa3b, v14
	v_exp_f32_e32 v14, v14
	v_cndmask_b32_e32 v15, v80, v65, vcc
	v_sqrt_f32_e64 v15, -v15
	v_cmp_lt_f32_e32 vcc, s76, v146
	v_add_f32_e32 v14, 1.0, v14
	v_mul_f32_e32 v199, v15, v9
	v_mfma_f32_32x32x16_bf16 v[18:33], v[56:59], v[118:121], v[18:33]
	v_rcp_f32_e32 v56, v14
	v_add_f32_e32 v14, v191, v17
	v_mul_f32_e32 v57, 0xbfb8aa3b, v14
	ds_read_b128 v[14:17], v187 offset:33376
	v_lshlrev_b32_e32 v9, 16, v81
	v_mul_f32_e32 v9, v56, v9
	s_waitcnt lgkmcnt(1)
	v_mfma_f32_32x32x16_bf16 v[34:49], v[10:13], v[130:133], v[34:49]
	v_mfma_f32_32x32x16_bf16 v[18:33], v[10:13], v[122:125], v[18:33]
	v_exp_f32_e32 v10, v57
	v_cndmask_b32_e32 v11, v154, v147, vcc
	v_sqrt_f32_e64 v11, -v11
	v_cmp_lt_f32_e32 vcc, s76, v156
	v_add_f32_e32 v10, 1.0, v10
	v_rcp_f32_e32 v10, v10
	v_cndmask_b32_e32 v12, v159, v158, vcc
	s_waitcnt lgkmcnt(0)
	v_mfma_f32_32x32x16_bf16 v[34:49], v[14:17], v[142:145], v[34:49]
	v_sqrt_f32_e64 v12, -v12
	v_mul_f32_e32 v204, v11, v9
	v_lshlrev_b32_e32 v9, 16, v155
	v_mul_f32_e32 v9, v10, v9
	v_mul_f32_e32 v202, v12, v9
	v_lshlrev_b32_e32 v11, 16, v195
	s_nop 5
	v_add_f32_e32 v10, v191, v34
	v_mfma_f32_32x32x16_bf16 v[18:33], v[14:17], v[138:141], v[18:33]
	v_mul_f32_e32 v10, 0xbfb8aa3b, v10
	v_exp_f32_e32 v10, v10
	s_nop 0
	v_add_f32_e32 v10, 1.0, v10
	v_rcp_f32_e32 v10, v10
	s_nop 6
	v_add_f32_e32 v9, v192, v18
	v_mul_f32_e32 v9, 0xbfb8aa3b, v9
	v_exp_f32_e32 v9, v9
	v_mul_f32_e32 v10, v10, v11
	v_add_f32_e32 v11, v192, v19
	v_mul_f32_e32 v11, 0xbfb8aa3b, v11
	v_add_f32_e32 v9, 1.0, v9
	v_rcp_f32_e32 v9, v9
	v_exp_f32_e32 v11, v11
	v_mul_f32_e32 v9, v194, v9
	v_exp_f32_e32 v80, v9
	v_mul_f32_e32 v9, 0x3fb17218, v9
	v_fmamk_f32 v12, v9, 0x3c088888, v186
	v_fmaak_f32 v12, v9, v12, 0x3e2aaaab
	v_add_f32_e32 v11, 1.0, v11
	v_fma_f32 v12, v9, v12, 0.5
	v_rcp_f32_e32 v11, v11
	v_fma_f32 v12, v9, v12, 1.0
	v_mul_f32_e32 v12, v9, v12
	v_fma_f32 v13, v80, v80, -1.0
	v_cmp_lt_f32_e32 vcc, s76, v9
	v_mul_f32_e32 v11, v194, v11
	v_exp_f32_e32 v146, v11
	v_cndmask_b32_e32 v9, v13, v12, vcc
	ds_read_u16 v13, v0 offset:34320
	v_add_f32_e32 v12, v191, v35
	v_mul_f32_e32 v12, 0xbfb8aa3b, v12
	v_mul_f32_e32 v11, 0x3fb17218, v11
	v_exp_f32_e32 v12, v12
	v_fmamk_f32 v14, v11, 0x3c088888, v186
	v_fmaak_f32 v14, v11, v14, 0x3e2aaaab
	v_fma_f32 v14, v11, v14, 0.5
	v_fma_f32 v14, v11, v14, 1.0
	v_sqrt_f32_e64 v9, -v9
	v_add_f32_e32 v12, 1.0, v12
	v_mul_f32_e32 v14, v11, v14
	v_fma_f32 v15, v146, v146, -1.0
	v_cmp_lt_f32_e32 vcc, s76, v11
	v_rcp_f32_e32 v12, v12
	v_mul_f32_e32 v196, v10, v9
	v_cndmask_b32_e32 v11, v15, v14, vcc
	v_sqrt_f32_e64 v11, -v11
	s_waitcnt lgkmcnt(0)
	v_lshlrev_b32_e32 v9, 16, v13
	v_mul_f32_e32 v9, v12, v9
	v_add_f32_e32 v10, v192, v20
	v_mul_f32_e32 v195, v9, v11
	ds_read_u16 v9, v0 offset:35360
	v_add_f32_e32 v11, v191, v36
	v_mul_f32_e32 v11, 0xbfb8aa3b, v11
	v_exp_f32_e32 v11, v11
	v_mul_f32_e32 v10, 0xbfb8aa3b, v10
	v_exp_f32_e32 v10, v10
	v_add_f32_e32 v11, 1.0, v11
	v_rcp_f32_e32 v11, v11
	v_add_f32_e32 v10, 1.0, v10
	v_rcp_f32_e32 v10, v10
	s_waitcnt lgkmcnt(0)
	v_lshlrev_b32_e32 v9, 16, v9
	v_mul_f32_e32 v9, v11, v9
	v_add_f32_e32 v11, v192, v21
	v_mul_f32_e32 v11, 0xbfb8aa3b, v11
	v_exp_f32_e32 v11, v11
	v_mul_f32_e32 v10, v194, v10
	v_exp_f32_e32 v81, v10
	v_mul_f32_e32 v10, 0x3fb17218, v10
	v_fmamk_f32 v12, v10, 0x3c088888, v186
	v_fmaak_f32 v12, v10, v12, 0x3e2aaaab
	v_add_f32_e32 v11, 1.0, v11
	v_fma_f32 v12, v10, v12, 0.5
	v_rcp_f32_e32 v11, v11
	v_fma_f32 v12, v10, v12, 1.0
	v_mul_f32_e32 v12, v10, v12
	v_fma_f32 v13, v81, v81, -1.0
	v_cmp_lt_f32_e32 vcc, s76, v10
	v_mul_f32_e32 v11, v194, v11
	v_exp_f32_e32 v198, v11
	v_cndmask_b32_e32 v10, v13, v12, vcc
	ds_read_u16 v13, v0 offset:36400
	v_add_f32_e32 v12, v191, v37
	v_mul_f32_e32 v12, 0xbfb8aa3b, v12
	v_mul_f32_e32 v11, 0x3fb17218, v11
	v_exp_f32_e32 v12, v12
	v_fmamk_f32 v14, v11, 0x3c088888, v186
	v_fmaak_f32 v14, v11, v14, 0x3e2aaaab
	v_fma_f32 v14, v11, v14, 0.5
	v_fma_f32 v14, v11, v14, 1.0
	v_sqrt_f32_e64 v10, -v10
	v_add_f32_e32 v12, 1.0, v12
	v_mul_f32_e32 v14, v11, v14
	v_fma_f32 v15, v198, v198, -1.0
	v_cmp_lt_f32_e32 vcc, s76, v11
	v_rcp_f32_e32 v12, v12
	v_mul_f32_e32 v214, v9, v10
	v_cndmask_b32_e32 v11, v15, v14, vcc
	v_sqrt_f32_e64 v11, -v11
	s_waitcnt lgkmcnt(0)
; __device__ __forceinline__ float bf2f(bf16_t b) { return __uint_as_float(((unsigned)b) << 16); }
; __device__ __forceinline__ float fast_sigmoid(float x) { return __builtin_amdgcn_rcpf(1.0f + __builtin_amdgcn_exp2f(-1.4426950408889634f * x)); }
; template <int DIR>
; __device__ __forceinline__ void scan_dir(PP p, const bf16_t* xs, const ScanW& w, ScanW& wn, int ndir, int nct, bool do_next, int n, int ct, int l31, int hl, int id, int rowbase, bool latent, float (&hf)[2][16]) {
;     ...
;         for (int i = 0; i < 16; ++i) {
;             const int token = 32 * rt + 8 * (i >> 2) + 4 * hl + (i & 3);
;             const float xv = bf2f(xs[token * XS + ch]);
;             const float rr = fast_sigmoid(ga[i] + ba), ii = fast_sigmoid(gi[i] + bi);
;             const float la2 = rr * sp8l2;
;             const float av = __builtin_amdgcn_exp2f(la2);
;             const float t2 = la2 * 1.3862943611f;
;             float em1p = t2 * (1.0f + t2 * (0.5f + t2 * (0.16666667f + t2 * (0.041666668f + t2 * 0.0083333333f)))), em1e = __builtin_fmaf(av, av, -1.0f);
;             asm volatile("" : "+v"(em1p), "+v"(em1e));
;             const float em1 = (t2 > -0.1f) ? em1p : em1e;
;             a[rt][i] = av; u[rt][i] = __builtin_amdgcn_sqrtf(-em1) * (ii * xv);
;         }
	v_lshlrev_b32_e32 v9, 16, v13
	v_mul_f32_e32 v9, v12, v9
	v_add_f32_e32 v10, v192, v22
	v_mul_f32_e32 v211, v11, v9
	ds_read_u16 v9, v0 offset:41600
	v_add_f32_e32 v11, v191, v38
	v_mul_f32_e32 v11, 0xbfb8aa3b, v11
	v_exp_f32_e32 v11, v11
	v_mul_f32_e32 v10, 0xbfb8aa3b, v10
	v_exp_f32_e32 v10, v10
	v_add_f32_e32 v11, 1.0, v11
	v_rcp_f32_e32 v11, v11
	v_add_f32_e32 v10, 1.0, v10
	v_rcp_f32_e32 v10, v10
	s_waitcnt lgkmcnt(0)
	v_lshlrev_b32_e32 v9, 16, v9
	v_mul_f32_e32 v9, v11, v9
	v_add_f32_e32 v11, v192, v23
	v_mul_f32_e32 v11, 0xbfb8aa3b, v11
	v_exp_f32_e32 v11, v11
	v_mul_f32_e32 v10, v194, v10
	v_exp_f32_e32 v147, v10
	v_mul_f32_e32 v10, 0x3fb17218, v10
	v_fmamk_f32 v12, v10, 0x3c088888, v186
	v_fmaak_f32 v12, v10, v12, 0x3e2aaaab
	v_add_f32_e32 v11, 1.0, v11
	v_fma_f32 v12, v10, v12, 0.5
	v_rcp_f32_e32 v11, v11
	v_fma_f32 v12, v10, v12, 1.0
	v_mul_f32_e32 v12, v10, v12
	v_fma_f32 v13, v147, v147, -1.0
	v_cmp_lt_f32_e32 vcc, s76, v10
	v_mul_f32_e32 v11, v194, v11
	v_exp_f32_e32 v201, v11
	v_cndmask_b32_e32 v10, v13, v12, vcc
	ds_read_u16 v13, v0 offset:42640
	v_add_f32_e32 v12, v191, v39
	v_mul_f32_e32 v12, 0xbfb8aa3b, v12
	v_mul_f32_e32 v11, 0x3fb17218, v11
	v_exp_f32_e32 v12, v12
	v_fmamk_f32 v14, v11, 0x3c088888, v186
	v_fmaak_f32 v14, v11, v14, 0x3e2aaaab
	v_fma_f32 v14, v11, v14, 0.5
	v_fma_f32 v14, v11, v14, 1.0
	v_sqrt_f32_e64 v10, -v10
	v_add_f32_e32 v12, 1.0, v12
	v_mul_f32_e32 v14, v11, v14
	v_fma_f32 v15, v201, v201, -1.0
	v_cmp_lt_f32_e32 vcc, s76, v11
	v_rcp_f32_e32 v12, v12
	v_mul_f32_e32 v206, v10, v9
	v_cndmask_b32_e32 v11, v15, v14, vcc
	v_sqrt_f32_e64 v11, -v11
	s_waitcnt lgkmcnt(0)
	v_lshlrev_b32_e32 v9, 16, v13
	v_mul_f32_e32 v9, v12, v9
	v_add_f32_e32 v10, v192, v24
	v_mul_f32_e32 v205, v11, v9
	ds_read_u16 v9, v0 offset:43680
	v_add_f32_e32 v11, v191, v40
	v_mul_f32_e32 v11, 0xbfb8aa3b, v11
	v_exp_f32_e32 v11, v11
	v_mul_f32_e32 v10, 0xbfb8aa3b, v10
	v_exp_f32_e32 v10, v10
	v_add_f32_e32 v11, 1.0, v11
	v_rcp_f32_e32 v11, v11
	v_add_f32_e32 v10, 1.0, v10
	v_rcp_f32_e32 v10, v10
	s_waitcnt lgkmcnt(0)
	v_lshlrev_b32_e32 v9, 16, v9
	v_mul_f32_e32 v9, v11, v9
	v_add_f32_e32 v11, v192, v25
	v_mul_f32_e32 v11, 0xbfb8aa3b, v11
	v_exp_f32_e32 v11, v11
	v_mul_f32_e32 v10, v194, v10
	v_exp_f32_e32 v200, v10
	v_mul_f32_e32 v10, 0x3fb17218, v10
	v_fmamk_f32 v12, v10, 0x3c088888, v186
	v_fmaak_f32 v12, v10, v12, 0x3e2aaaab
	v_add_f32_e32 v11, 1.0, v11
	v_fma_f32 v12, v10, v12, 0.5
	v_rcp_f32_e32 v11, v11
	v_fma_f32 v12, v10, v12, 1.0
	v_mul_f32_e32 v12, v10, v12
	v_fma_f32 v13, v200, v200, -1.0
	v_cmp_lt_f32_e32 vcc, s76, v10
	v_mul_f32_e32 v11, v194, v11
	v_exp_f32_e32 v207, v11
	v_cndmask_b32_e32 v10, v13, v12, vcc
	ds_read_u16 v13, v0 offset:44720
	v_add_f32_e32 v12, v191, v41
	v_mul_f32_e32 v12, 0xbfb8aa3b, v12
	v_mul_f32_e32 v11, 0x3fb17218, v11
	v_exp_f32_e32 v12, v12
	v_fmamk_f32 v14, v11, 0x3c088888, v186
	v_fmaak_f32 v14, v11, v14, 0x3e2aaaab
	v_fma_f32 v14, v11, v14, 0.5
	v_fma_f32 v14, v11, v14, 1.0
	v_sqrt_f32_e64 v10, -v10
	v_add_f32_e32 v12, 1.0, v12
	v_mul_f32_e32 v14, v11, v14
	v_fma_f32 v15, v207, v207, -1.0
	v_cmp_lt_f32_e32 vcc, s76, v11
	v_rcp_f32_e32 v12, v12
	v_mul_f32_e32 v222, v10, v9
	v_cndmask_b32_e32 v11, v15, v14, vcc
	v_sqrt_f32_e64 v11, -v11
	s_waitcnt lgkmcnt(0)
	v_lshlrev_b32_e32 v9, 16, v13
	v_mul_f32_e32 v9, v12, v9
	v_add_f32_e32 v10, v192, v26
	v_mul_f32_e32 v221, v11, v9
	ds_read_u16 v9, v0 offset:49920
	v_add_f32_e32 v11, v191, v42
	v_mul_f32_e32 v11, 0xbfb8aa3b, v11
	v_exp_f32_e32 v11, v11
	v_mul_f32_e32 v10, 0xbfb8aa3b, v10
	v_exp_f32_e32 v10, v10
	v_add_f32_e32 v11, 1.0, v11
	v_rcp_f32_e32 v11, v11
	v_add_f32_e32 v10, 1.0, v10
	v_rcp_f32_e32 v10, v10
	s_waitcnt lgkmcnt(0)
	v_lshlrev_b32_e32 v9, 16, v9
	v_mul_f32_e32 v9, v11, v9
	v_add_f32_e32 v11, v192, v27
	v_mul_f32_e32 v11, 0xbfb8aa3b, v11
	v_exp_f32_e32 v11, v11
	v_mul_f32_e32 v10, v194, v10
	v_exp_f32_e32 v203, v10
	v_mul_f32_e32 v10, 0x3fb17218, v10
	v_fmamk_f32 v12, v10, 0x3c088888, v186
	v_fmaak_f32 v12, v10, v12, 0x3e2aaaab
	v_add_f32_e32 v11, 1.0, v11
	v_fma_f32 v12, v10, v12, 0.5
	v_rcp_f32_e32 v11, v11
	v_fma_f32 v12, v10, v12, 1.0
	v_mul_f32_e32 v12, v10, v12
	v_fma_f32 v13, v203, v203, -1.0
	v_cmp_lt_f32_e32 vcc, s76, v10
	v_mul_f32_e32 v11, v194, v11
	v_exp_f32_e32 v210, v11
	v_cndmask_b32_e32 v10, v13, v12, vcc
	ds_read_u16 v13, v0 offset:50960
	v_add_f32_e32 v12, v191, v43
	v_mul_f32_e32 v12, 0xbfb8aa3b, v12
	v_mul_f32_e32 v11, 0x3fb17218, v11
	v_exp_f32_e32 v12, v12
	v_fmamk_f32 v14, v11, 0x3c088888, v186
	v_fmaak_f32 v14, v11, v14, 0x3e2aaaab
	v_fma_f32 v14, v11, v14, 0.5
	v_fma_f32 v14, v11, v14, 1.0
	v_sqrt_f32_e64 v10, -v10
	v_add_f32_e32 v12, 1.0, v12
	v_mul_f32_e32 v14, v11, v14
	v_fma_f32 v15, v210, v210, -1.0
	v_cmp_lt_f32_e32 vcc, s76, v11
	v_rcp_f32_e32 v12, v12
	v_mul_f32_e32 v216, v10, v9
	v_cndmask_b32_e32 v11, v15, v14, vcc
	v_sqrt_f32_e64 v11, -v11
	s_waitcnt lgkmcnt(0)
	v_lshlrev_b32_e32 v9, 16, v13
	v_mul_f32_e32 v9, v12, v9
	v_add_f32_e32 v10, v192, v28
	v_mul_f32_e32 v215, v11, v9
	ds_read_u16 v9, v0 offset:52000
	v_add_f32_e32 v11, v191, v44
	v_mul_f32_e32 v11, 0xbfb8aa3b, v11
	v_exp_f32_e32 v11, v11
	v_mul_f32_e32 v10, 0xbfb8aa3b, v10
	v_exp_f32_e32 v10, v10
	v_add_f32_e32 v11, 1.0, v11
	v_rcp_f32_e32 v11, v11
	v_add_f32_e32 v10, 1.0, v10
	v_rcp_f32_e32 v10, v10
	s_waitcnt lgkmcnt(0)
; __device__ __forceinline__ float bf2f(bf16_t b) { return __uint_as_float(((unsigned)b) << 16); }
; __device__ __forceinline__ float fast_sigmoid(float x) { return __builtin_amdgcn_rcpf(1.0f + __builtin_amdgcn_exp2f(-1.4426950408889634f * x)); }
; template <int DIR>
; __device__ __forceinline__ void scan_dir(PP p, const bf16_t* xs, const ScanW& w, ScanW& wn, int ndir, int nct, bool do_next, int n, int ct, int l31, int hl, int id, int rowbase, bool latent, float (&hf)[2][16]) {
;     ...
;         for (int i = 0; i < 16; ++i) {
;             const int token = 32 * rt + 8 * (i >> 2) + 4 * hl + (i & 3);
;             const float xv = bf2f(xs[token * XS + ch]);
;             const float rr = fast_sigmoid(ga[i] + ba), ii = fast_sigmoid(gi[i] + bi);
;             const float la2 = rr * sp8l2;
;             const float av = __builtin_amdgcn_exp2f(la2);
;             const float t2 = la2 * 1.3862943611f;
;             float em1p = t2 * (1.0f + t2 * (0.5f + t2 * (0.16666667f + t2 * (0.041666668f + t2 * 0.0083333333f)))), em1e = __builtin_fmaf(av, av, -1.0f);
;             asm volatile("" : "+v"(em1p), "+v"(em1e));
;             const float em1 = (t2 > -0.1f) ? em1p : em1e;
;             a[rt][i] = av; u[rt][i] = __builtin_amdgcn_sqrtf(-em1) * (ii * xv);
;         }
;     }
;     float Ao[8], Ho[8], Ap[8], Hp[8];
; #pragma unroll
;     for (int k = 0; k < 8; ++k) {
;         const int rt = k >> 2, g = k & 3;
;         float H = 0.f, A = 1.f;
; #pragma unroll
;         for (int jj = 0; jj < 4; ++jj) { const int j = DIR ? 3 - jj : jj; const float av = a[rt][4 * g + j]; H = av * H + u[rt][4 * g + j]; A *= av; }
;         Ao[k] = A; Ho[k] = H; Ap[k] = __shfl_xor(A, 32); Hp[k] = __shfl_xor(H, 32);
	v_lshlrev_b32_e32 v9, 16, v9
	v_mul_f32_e32 v9, v11, v9
	v_add_f32_e32 v11, v192, v29
	v_mul_f32_e32 v11, 0xbfb8aa3b, v11
	v_exp_f32_e32 v11, v11
	v_mul_f32_e32 v10, v194, v10
	v_exp_f32_e32 v208, v10
	v_mul_f32_e32 v10, 0x3fb17218, v10
	v_fmamk_f32 v12, v10, 0x3c088888, v186
	v_fmaak_f32 v12, v10, v12, 0x3e2aaaab
	v_add_f32_e32 v11, 1.0, v11
	v_fma_f32 v12, v10, v12, 0.5
	v_rcp_f32_e32 v11, v11
	v_fma_f32 v12, v10, v12, 1.0
	v_mul_f32_e32 v12, v10, v12
	v_fma_f32 v13, v208, v208, -1.0
	v_cmp_lt_f32_e32 vcc, s76, v10
	v_mul_f32_e32 v11, v194, v11
	v_exp_f32_e32 v218, v11
	v_cndmask_b32_e32 v10, v13, v12, vcc
	ds_read_u16 v13, v0 offset:53040
	v_add_f32_e32 v12, v191, v45
	v_mul_f32_e32 v12, 0xbfb8aa3b, v12
	v_mul_f32_e32 v11, 0x3fb17218, v11
	v_exp_f32_e32 v12, v12
	v_fmamk_f32 v14, v11, 0x3c088888, v186
	v_fmaak_f32 v14, v11, v14, 0x3e2aaaab
	v_fma_f32 v14, v11, v14, 0.5
	v_fma_f32 v14, v11, v14, 1.0
	v_sqrt_f32_e64 v10, -v10
	v_add_f32_e32 v12, 1.0, v12
	v_mul_f32_e32 v14, v11, v14
	v_fma_f32 v15, v218, v218, -1.0
	v_cmp_lt_f32_e32 vcc, s76, v11
	v_rcp_f32_e32 v12, v12
	v_mul_f32_e32 v227, v10, v9
	v_cndmask_b32_e32 v11, v15, v14, vcc
	v_sqrt_f32_e64 v11, -v11
	s_waitcnt lgkmcnt(0)
	v_lshlrev_b32_e32 v9, 16, v13
	v_mul_f32_e32 v9, v12, v9
	v_add_f32_e32 v10, v192, v30
	v_mul_f32_e32 v226, v11, v9
	ds_read_u16 v9, v0 offset:58240
	v_add_f32_e32 v11, v191, v46
	v_mul_f32_e32 v11, 0xbfb8aa3b, v11
	v_exp_f32_e32 v11, v11
	v_mul_f32_e32 v10, 0xbfb8aa3b, v10
	v_exp_f32_e32 v10, v10
	v_add_f32_e32 v11, 1.0, v11
	v_rcp_f32_e32 v11, v11
	v_add_f32_e32 v10, 1.0, v10
	v_rcp_f32_e32 v10, v10
	s_waitcnt lgkmcnt(0)
	v_lshlrev_b32_e32 v9, 16, v9
	v_mul_f32_e32 v9, v11, v9
	v_add_f32_e32 v11, v192, v31
	v_mul_f32_e32 v11, 0xbfb8aa3b, v11
	v_exp_f32_e32 v11, v11
	v_mul_f32_e32 v10, v194, v10
	v_exp_f32_e32 v213, v10
	v_mul_f32_e32 v10, 0x3fb17218, v10
	v_fmamk_f32 v12, v10, 0x3c088888, v186
	v_fmaak_f32 v12, v10, v12, 0x3e2aaaab
	v_add_f32_e32 v11, 1.0, v11
	v_fma_f32 v12, v10, v12, 0.5
	v_rcp_f32_e32 v11, v11
	v_fma_f32 v12, v10, v12, 1.0
	v_mul_f32_e32 v12, v10, v12
	v_fma_f32 v13, v213, v213, -1.0
	v_cmp_lt_f32_e32 vcc, s76, v10
	v_mul_f32_e32 v11, v194, v11
	v_exp_f32_e32 v220, v11
	v_cndmask_b32_e32 v10, v13, v12, vcc
	ds_read_u16 v13, v0 offset:59280
	v_add_f32_e32 v12, v191, v47
	v_mul_f32_e32 v12, 0xbfb8aa3b, v12
	v_mul_f32_e32 v11, 0x3fb17218, v11
	v_exp_f32_e32 v12, v12
	v_fmamk_f32 v14, v11, 0x3c088888, v186
	v_fmaak_f32 v14, v11, v14, 0x3e2aaaab
	v_fma_f32 v14, v11, v14, 0.5
	v_fma_f32 v14, v11, v14, 1.0
	v_sqrt_f32_e64 v10, -v10
	v_add_f32_e32 v12, 1.0, v12
	v_mul_f32_e32 v14, v11, v14
	v_fma_f32 v15, v220, v220, -1.0
	v_cmp_lt_f32_e32 vcc, s76, v11
	v_rcp_f32_e32 v12, v12
	v_mul_f32_e32 v224, v10, v9
	v_cndmask_b32_e32 v11, v15, v14, vcc
	v_sqrt_f32_e64 v11, -v11
	s_waitcnt lgkmcnt(0)
	v_lshlrev_b32_e32 v9, 16, v13
	v_mul_f32_e32 v9, v12, v9
	v_add_f32_e32 v10, v192, v32
	v_mul_f32_e32 v223, v11, v9
	ds_read_u16 v9, v0 offset:60320
	v_add_f32_e32 v11, v191, v48
	v_mul_f32_e32 v11, 0xbfb8aa3b, v11
	v_exp_f32_e32 v11, v11
	v_mul_f32_e32 v10, 0xbfb8aa3b, v10
	v_exp_f32_e32 v10, v10
	v_add_f32_e32 v11, 1.0, v11
	v_rcp_f32_e32 v11, v11
	v_add_f32_e32 v10, 1.0, v10
	v_rcp_f32_e32 v10, v10
	s_waitcnt lgkmcnt(0)
	v_lshlrev_b32_e32 v9, 16, v9
	v_mul_f32_e32 v9, v11, v9
	v_add_f32_e32 v11, v192, v33
	v_mul_f32_e32 v11, 0xbfb8aa3b, v11
	v_exp_f32_e32 v11, v11
	v_mul_f32_e32 v10, v194, v10
	v_exp_f32_e32 v219, v10
	v_mul_f32_e32 v10, 0x3fb17218, v10
	v_fmamk_f32 v12, v10, 0x3c088888, v186
	v_fmaak_f32 v12, v10, v12, 0x3e2aaaab
	v_add_f32_e32 v11, 1.0, v11
	v_fma_f32 v12, v10, v12, 0.5
	v_rcp_f32_e32 v11, v11
	v_fma_f32 v12, v10, v12, 1.0
	v_mul_f32_e32 v12, v10, v12
	v_fma_f32 v13, v219, v219, -1.0
	v_cmp_lt_f32_e32 vcc, s76, v10
	v_mul_f32_e32 v11, v194, v11
	v_exp_f32_e32 v225, v11
	v_cndmask_b32_e32 v10, v13, v12, vcc
	v_add_f32_e32 v12, v191, v49
	v_mul_f32_e32 v12, 0xbfb8aa3b, v12
	v_mul_f32_e32 v11, 0x3fb17218, v11
	v_exp_f32_e32 v12, v12
	v_fmamk_f32 v13, v11, 0x3c088888, v186
	v_fmaak_f32 v13, v11, v13, 0x3e2aaaab
	v_fma_f32 v13, v11, v13, 0.5
	ds_read_u16 v0, v0 offset:61360
	v_fma_f32 v13, v11, v13, 1.0
	v_add_f32_e32 v12, 1.0, v12
	v_mul_f32_e32 v13, v11, v13
	v_fma_f32 v14, v225, v225, -1.0
	v_cmp_lt_f32_e32 vcc, s76, v11
	v_sqrt_f32_e64 v10, -v10
	v_rcp_f32_e32 v12, v12
	s_waitcnt lgkmcnt(0)
	v_lshlrev_b32_e32 v0, 16, v0
	v_cndmask_b32_e32 v11, v14, v13, vcc
	v_sqrt_f32_e64 v11, -v11
	v_mul_f32_e32 v229, v10, v9
	v_mul_f32_e32 v0, v12, v0
	v_and_b32_e32 v9, 64, v188
	v_mul_f32_e32 v228, v11, v0
	v_xor_b32_e32 v0, 32, v188
	v_add_u32_e32 v9, 64, v9
	v_cmp_lt_i32_e32 vcc, v0, v9
	v_fma_f32 v9, 0, v50, v2
	v_fma_f32 v9, v52, v9, v3
	v_fma_f32 v9, v51, v9, v4
	v_fma_f32 v34, v54, v9, v5
	v_fma_f32 v9, 0, v53, v6
	v_fma_f32 v9, v55, v9, v7
	v_fma_f32 v9, v67, v9, v8
	v_fma_f32 v255, v69, v9, v76
	v_fma_f32 v9, 0, v68, v74
	v_fma_f32 v9, v71, v9, v73
	v_mul_f32_e32 v10, v50, v52
	v_fma_f32 v9, v70, v9, v209
	v_mul_f32_e32 v10, v51, v10
	v_fma_f32 v251, v75, v9, v217
	v_fma_f32 v9, 0, v72, v197
	v_mul_f32_e32 v35, v54, v10
	v_mul_f32_e32 v10, v53, v55
	v_fma_f32 v9, v78, v9, v199
	v_mul_f32_e32 v10, v67, v10
	v_fma_f32 v9, v77, v9, v204
	v_mul_f32_e32 v154, v69, v10
	v_mul_f32_e32 v10, v68, v71
	v_fma_f32 v247, v79, v9, v202
	v_fma_f32 v9, 0, v80, v196
	v_mul_f32_e32 v10, v70, v10
	v_fma_f32 v9, v146, v9, v195
	v_mul_f32_e32 v253, v75, v10
	v_mul_f32_e32 v10, v72, v78
	v_fma_f32 v9, v81, v9, v214
	v_mul_f32_e32 v10, v77, v10
	v_fma_f32 v243, v198, v9, v211
	v_fma_f32 v9, 0, v147, v206
	v_mul_f32_e32 v249, v79, v10
	v_mul_f32_e32 v10, v80, v146
	v_fma_f32 v9, v201, v9, v205
	v_mul_f32_e32 v10, v81, v10
	v_fma_f32 v9, v200, v9, v222
	v_mul_f32_e32 v245, v198, v10
	v_mul_f32_e32 v10, v147, v201
	v_fma_f32 v239, v207, v9, v221
	v_fma_f32 v9, 0, v203, v216
	v_mul_f32_e32 v10, v200, v10
	v_fma_f32 v9, v210, v9, v215
	v_mul_f32_e32 v241, v207, v10
	v_mul_f32_e32 v10, v203, v210
	v_fma_f32 v9, v208, v9, v227
	v_mul_f32_e32 v10, v208, v10
	v_fma_f32 v234, v218, v9, v226
	v_fma_f32 v9, 0, v213, v224
	v_mul_f32_e32 v236, v218, v10
	v_fma_f32 v9, v220, v9, v223
	v_mul_f32_e32 v10, v213, v220
	v_cndmask_b32_e32 v0, v188, v0, vcc
	v_fma_f32 v9, v219, v9, v229
	v_mul_f32_e32 v10, v219, v10
	v_lshlrev_b32_e32 v0, 2, v0
	v_fma_f32 v230, v225, v9, v228
	v_mul_f32_e32 v231, v225, v10
	ds_bpermute_b32 v36, v0, v35
	ds_bpermute_b32 v37, v0, v34
	ds_bpermute_b32 v155, v0, v154
	ds_bpermute_b32 v212, v0, v255
	ds_bpermute_b32 v254, v0, v253
	ds_bpermute_b32 v252, v0, v251
	ds_bpermute_b32 v250, v0, v249
	ds_bpermute_b32 v248, v0, v247
	ds_bpermute_b32 v246, v0, v245
	ds_bpermute_b32 v244, v0, v243
	ds_bpermute_b32 v242, v0, v241
	ds_bpermute_b32 v240, v0, v239
	ds_bpermute_b32 v237, v0, v236
	ds_bpermute_b32 v235, v0, v234
	ds_bpermute_b32 v232, v0, v231
	ds_bpermute_b32 v233, v0, v230
	v_cndmask_b32_e64 v0, 0, 1, s[22:23]
	v_cmp_ne_u32_e64 s[4:5], 1, v0
	s_andn2_b64 vcc, exec, s[22:23]
	s_cbranch_vccnz .LBB0_380
; __device__ __forceinline__ void scan_loadw(PP p, int dir, int n, int ct, int l31, int hl, ScanW& w) {
;     unsigned chv = (unsigned)(32 * ct + l31); asm volatile("" : "+v"(chv));
;     const unsigned ch = (unsigned)(dir * 512 + 64 * n) + chv;
;     w.ba = p->lru_b_a[ch]; w.bi = p->lru_b_i[ch];
;     w.sp8l2 = ((const float*)(p->ws + WS_SP8))[ch] * 1.4426950408889634f;
;     const bf16_t* wa_b = (const bf16_t*)(p->ws + WS_LRU) + (size_t)((dir * 2 + 0) * 8 + n) * 4096;
;     const bf16_t* wi_b = (const bf16_t*)(p->ws + WS_LRU) + (size_t)((dir * 2 + 1) * 8 + n) * 4096;
;     const unsigned lo = chv * 64u + 8u * (unsigned)hl;
; #pragma unroll
;     for (int st = 0; st < 4; ++st) { w.wfa[st] = *(const bf16x8*)(wa_b + lo + 16 * st); w.wfi[st] = *(const bf16x8*)(wi_b + lo + 16 * st); }
; }
	v_or_b32_e32 v9, s48, v148
	s_load_dwordx2 s[48:49], s[8:9], 0x58
	s_load_dwordx2 s[82:83], s[8:9], 0x68
	v_add_u32_e32 v0, s50, v9
	v_lshlrev_b64 v[10:11], 2, v[0:1]
	v_lshl_or_b32 v0, v9, 6, v149
	s_waitcnt lgkmcnt(0)
	v_lshl_add_u64 v[12:13], s[48:49], 0, v[10:11]
	global_load_dword v189, v[12:13], off
	v_lshl_add_u64 v[12:13], s[82:83], 0, v[10:11]
	global_load_dword v190, v[12:13], off
	v_lshl_add_u64 v[10:11], s[12:13], 0, v[10:11]
	v_lshlrev_b64 v[12:13], 1, v[0:1]
	v_lshl_add_u64 v[14:15], s[20:21], 0, v[12:13]
	v_lshl_add_u64 v[12:13], s[16:17], 0, v[12:13]
	global_load_dword v0, v[10:11], off
	global_load_dwordx4 v[82:85], v[14:15], off
	global_load_dwordx4 v[86:89], v[14:15], off offset:32
	global_load_dwordx4 v[90:93], v[14:15], off offset:64
	global_load_dwordx4 v[94:97], v[12:13], off offset:32
	global_load_dwordx4 v[102:105], v[12:13], off offset:64
	global_load_dwordx4 v[98:101], v[12:13], off
	global_load_dwordx4 v[106:109], v[14:15], off offset:96
	global_load_dwordx4 v[110:113], v[12:13], off offset:96
	s_waitcnt vmcnt(8)
	v_mul_f32_e32 v193, 0x3fb8aa3b, v0

; __device__ __forceinline__ float bf2f(bf16_t b) { return __uint_as_float(((unsigned)b) << 16); }
; __device__ __forceinline__ float fast_sigmoid(float x) { return __builtin_amdgcn_rcpf(1.0f + __builtin_amdgcn_exp2f(-1.4426950408889634f * x)); }
; template <int DIR>
; __device__ __forceinline__ void scan_dir(PP p, const bf16_t* xs, const ScanW& w, ScanW& wn, int ndir, int nct, bool do_next, int n, int ct, int l31, int hl, int id, int rowbase, bool latent, float (&hf)[2][16]) {
;     ...
;     for (int rt = 0; rt < 2; ++rt) {
;         bf16x8 af[4];
; #pragma unroll
;         for (int st = 0; st < 4; ++st) af[st] = *(const bf16x8*)(xs + (32 * rt + l31) * XS + 64 * n + 16 * st + 8 * hl);
;         f32x16 ga, gi;
; #pragma unroll
;         for (int i = 0; i < 16; ++i) { ga[i] = 0.f; gi[i] = 0.f; }
; #pragma unroll
;         for (int st = 0; st < 4; ++st) { ga = __builtin_amdgcn_mfma_f32_32x32x16_bf16(af[st], wfa[st], ga, 0, 0, 0); gi = __builtin_amdgcn_mfma_f32_32x32x16_bf16(af[st], wfi[st], gi, 0, 0, 0); }
; #pragma unroll
;         for (int i = 0; i < 16; ++i) {
;             const int token = 32 * rt + 8 * (i >> 2) + 4 * hl + (i & 3);
;             const float xv = bf2f(xs[token * XS + ch]);
;             const float rr = fast_sigmoid(ga[i] + ba), ii = fast_sigmoid(gi[i] + bi);
;             const float la2 = rr * sp8l2;
;             const float av = __builtin_amdgcn_exp2f(la2);
;             const float t2 = la2 * 1.3862943611f;
;             float em1p = t2 * (1.0f + t2 * (0.5f + t2 * (0.16666667f + t2 * (0.041666668f + t2 * 0.0083333333f)))), em1e = __builtin_fmaf(av, av, -1.0f);
;             asm volatile("" : "+v"(em1p), "+v"(em1e));
;             const float em1 = (t2 > -0.1f) ? em1p : em1e;
;             a[rt][i] = av; u[rt][i] = __builtin_amdgcn_sqrtf(-em1) * (ii * xv);
;         }
.LBB0_445:
	ds_read_b128 v[34:37], v187
	v_lshl_or_b32 v146, s80, 5, v150
	v_lshl_add_u32 v74, v146, 1, 0
	v_add_u32_e32 v0, v74, v151
	ds_read_u16 v75, v0
	ds_read_b128 v[66:69], v187 offset:32
	ds_read_b128 v[70:73], v187 offset:64
	v_add_u32_e32 v213, v74, v152
	s_and_b64 s[4:5], s[22:23], s[44:45]
	s_waitcnt vmcnt(7) lgkmcnt(3)
	v_mfma_f32_32x32x16_bf16 v[50:65], v[34:37], v[82:85], 0
	s_waitcnt vmcnt(2)
	v_mfma_f32_32x32x16_bf16 v[34:49], v[34:37], v[98:101], 0
	s_waitcnt lgkmcnt(1)
	v_mfma_f32_32x32x16_bf16 v[50:65], v[66:69], v[86:89], v[50:65]
	v_mfma_f32_32x32x16_bf16 v[34:49], v[66:69], v[94:97], v[34:49]
	ds_read_b128 v[66:69], v187 offset:96
	s_waitcnt lgkmcnt(1)
	v_mfma_f32_32x32x16_bf16 v[50:65], v[70:73], v[90:93], v[50:65]
	v_mfma_f32_32x32x16_bf16 v[34:49], v[70:73], v[102:105], v[34:49]
	s_waitcnt vmcnt(1) lgkmcnt(0)
	v_mfma_f32_32x32x16_bf16 v[50:65], v[66:69], v[106:109], v[50:65]
	s_waitcnt vmcnt(0)
	v_mfma_f32_32x32x16_bf16 v[34:49], v[66:69], v[110:113], v[34:49]
	s_nop 9
	v_add_f32_e32 v50, v189, v50
	v_mul_f32_e32 v50, 0xbfb8aa3b, v50
	v_exp_f32_e32 v50, v50
	v_add_f32_e32 v51, v189, v51
	v_mul_f32_e32 v51, 0xbfb8aa3b, v51
	v_exp_f32_e32 v51, v51
	v_add_f32_e32 v50, 1.0, v50
	v_add_f32_e32 v34, v190, v34
	v_mul_f32_e32 v34, 0xbfb8aa3b, v34
	v_exp_f32_e32 v34, v34
	v_rcp_f32_e32 v50, v50
	v_add_f32_e32 v35, v190, v35
	v_mul_f32_e32 v35, 0xbfb8aa3b, v35
	v_add_f32_e32 v34, 1.0, v34
	v_mul_f32_e32 v50, v193, v50
	v_rcp_f32_e32 v67, v34
	v_exp_f32_e32 v34, v50
	v_mul_f32_e32 v50, 0x3fb17218, v50
	v_fmamk_f32 v68, v50, 0x3c088888, v186
	v_fmaak_f32 v68, v50, v68, 0x3e2aaaab
	v_exp_f32_e32 v35, v35
	v_add_f32_e32 v51, 1.0, v51
	v_fma_f32 v68, v50, v68, 0.5
	v_rcp_f32_e32 v51, v51
	v_fma_f32 v68, v50, v68, 1.0
	v_mul_f32_e32 v68, v50, v68
	v_fma_f32 v69, v34, v34, -1.0
	v_cmp_lt_f32_e32 vcc, s76, v50
	v_add_f32_e32 v35, 1.0, v35
	v_lshlrev_b32_e32 v66, 16, v75
	v_cndmask_b32_e32 v50, v69, v68, vcc
	v_rcp_f32_e32 v69, v35
	v_mul_f32_e32 v35, v193, v51
	v_exp_f32_e32 v147, v35
	v_mul_f32_e32 v35, 0x3fb17218, v35
	v_fmamk_f32 v51, v35, 0x3c088888, v186
	v_fmaak_f32 v51, v35, v51, 0x3e2aaaab
	v_mul_f32_e32 v66, v67, v66
	v_add_u32_e32 v67, v74, v185
	ds_read_u16 v68, v67
	v_fma_f32 v51, v35, v51, 0.5
	v_fma_f32 v51, v35, v51, 1.0
	v_sqrt_f32_e64 v50, -v50
	v_mul_f32_e32 v51, v35, v51
	v_fma_f32 v70, v147, v147, -1.0
	v_cmp_lt_f32_e32 vcc, s76, v35
	v_add_f32_e32 v36, v190, v36
	v_mul_f32_e32 v36, 0xbfb8aa3b, v36
	v_cndmask_b32_e32 v35, v70, v51, vcc
	v_sqrt_f32_e64 v51, -v35
	v_exp_f32_e32 v36, v36
	v_mul_f32_e32 v35, v66, v50
	s_waitcnt lgkmcnt(0)
	v_lshlrev_b32_e32 v50, 16, v68
	v_mul_f32_e32 v50, v69, v50
	v_mul_f32_e32 v195, v50, v51
	ds_read_u16 v50, v67 offset:1040
	v_add_f32_e32 v36, 1.0, v36
	v_rcp_f32_e32 v36, v36
	v_add_f32_e32 v51, v189, v52
	v_mul_f32_e32 v51, 0xbfb8aa3b, v51
	v_exp_f32_e32 v51, v51
	s_waitcnt lgkmcnt(0)
	v_lshlrev_b32_e32 v50, 16, v50
	v_mul_f32_e32 v36, v36, v50
	v_add_f32_e32 v50, v189, v53
	v_mul_f32_e32 v50, 0xbfb8aa3b, v50
	v_exp_f32_e32 v50, v50
	v_add_f32_e32 v51, 1.0, v51
	v_rcp_f32_e32 v51, v51
	v_add_f32_e32 v37, v190, v37
	v_add_f32_e32 v50, 1.0, v50
	v_rcp_f32_e32 v50, v50
	v_mul_f32_e32 v51, v193, v51
	v_exp_f32_e32 v196, v51
	v_mul_f32_e32 v51, 0x3fb17218, v51
	v_fmamk_f32 v52, v51, 0x3c088888, v186
	v_fmaak_f32 v52, v51, v52, 0x3e2aaaab
	v_mul_f32_e32 v50, v193, v50
	v_fma_f32 v52, v51, v52, 0.5
	v_mul_f32_e32 v37, 0xbfb8aa3b, v37
	v_exp_f32_e32 v198, v50
	v_mul_f32_e32 v50, 0x3fb17218, v50
	v_fma_f32 v52, v51, v52, 1.0
	v_exp_f32_e32 v37, v37
	v_fmamk_f32 v53, v50, 0x3c088888, v186
	v_mul_f32_e32 v52, v51, v52
	v_fma_f32 v66, v196, v196, -1.0
	v_fmaak_f32 v53, v50, v53, 0x3e2aaaab
	v_cmp_lt_f32_e32 vcc, s76, v51
	v_fma_f32 v53, v50, v53, 0.5
	v_fma_f32 v53, v50, v53, 1.0
	v_cndmask_b32_e32 v51, v66, v52, vcc
	ds_read_u16 v52, v67 offset:2080
	v_sqrt_f32_e64 v51, -v51
	v_add_f32_e32 v37, 1.0, v37
	v_mul_f32_e32 v53, v50, v53
	v_fma_f32 v66, v198, v198, -1.0
	v_cmp_lt_f32_e32 vcc, s76, v50
	v_rcp_f32_e32 v37, v37
	v_mul_f32_e32 v197, v36, v51
	v_cndmask_b32_e32 v50, v66, v53, vcc
	v_sqrt_f32_e64 v50, -v50
	s_waitcnt lgkmcnt(0)
	v_lshlrev_b32_e32 v36, 16, v52
	v_mul_f32_e32 v36, v37, v36
	v_add_f32_e32 v38, v190, v38
	v_mul_f32_e32 v199, v50, v36
	ds_read_u16 v36, v213
	v_mul_f32_e32 v38, 0xbfb8aa3b, v38
	v_exp_f32_e32 v38, v38
	v_add_f32_e32 v37, v189, v54
	v_mul_f32_e32 v37, 0xbfb8aa3b, v37
	v_exp_f32_e32 v37, v37
	s_waitcnt lgkmcnt(0)
	v_lshlrev_b32_e32 v50, 16, v36
	v_add_f32_e32 v36, 1.0, v38
	v_rcp_f32_e32 v38, v36
	v_add_f32_e32 v37, 1.0, v37
	v_rcp_f32_e32 v37, v37
	v_add_f32_e32 v39, v190, v39
	v_mul_f32_e32 v50, v38, v50
	v_add_f32_e32 v38, v189, v55
	v_mul_f32_e32 v38, 0xbfb8aa3b, v38
	v_exp_f32_e32 v38, v38
	v_mul_f32_e32 v37, v193, v37
	v_exp_f32_e32 v36, v37
	v_mul_f32_e32 v37, 0x3fb17218, v37
	v_fmamk_f32 v51, v37, 0x3c088888, v186
	v_fmaak_f32 v51, v37, v51, 0x3e2aaaab
	v_add_f32_e32 v38, 1.0, v38
	v_fma_f32 v51, v37, v51, 0.5
	v_rcp_f32_e32 v38, v38
	v_fma_f32 v51, v37, v51, 1.0
	v_mul_f32_e32 v39, 0xbfb8aa3b, v39
	v_mul_f32_e32 v51, v37, v51
	v_fma_f32 v52, v36, v36, -1.0
	v_exp_f32_e32 v39, v39
	v_cmp_lt_f32_e32 vcc, s76, v37
	v_add_f32_e32 v40, v190, v40
	v_add_f32_e32 v39, 1.0, v39
	v_cndmask_b32_e32 v37, v52, v51, vcc
	ds_read_u16 v51, v213 offset:1040
	v_mul_f32_e32 v52, v193, v38
	v_exp_f32_e32 v38, v52
	v_mul_f32_e32 v52, 0x3fb17218, v52
	v_sqrt_f32_e64 v37, -v37
	v_fmamk_f32 v53, v52, 0x3c088888, v186
	v_rcp_f32_e32 v39, v39
	v_fmaak_f32 v53, v52, v53, 0x3e2aaaab
	v_mul_f32_e32 v40, 0xbfb8aa3b, v40
	v_fma_f32 v53, v52, v53, 0.5
	v_exp_f32_e32 v40, v40
	v_fma_f32 v53, v52, v53, 1.0
	v_mul_f32_e32 v53, v52, v53
	v_fma_f32 v54, v38, v38, -1.0
	v_mul_f32_e32 v37, v37, v50
	s_waitcnt lgkmcnt(0)
; __device__ __forceinline__ float bf2f(bf16_t b) { return __uint_as_float(((unsigned)b) << 16); }
; __device__ __forceinline__ float fast_sigmoid(float x) { return __builtin_amdgcn_rcpf(1.0f + __builtin_amdgcn_exp2f(-1.4426950408889634f * x)); }
; template <int DIR>
; __device__ __forceinline__ void scan_dir(PP p, const bf16_t* xs, const ScanW& w, ScanW& wn, int ndir, int nct, bool do_next, int n, int ct, int l31, int hl, int id, int rowbase, bool latent, float (&hf)[2][16]) {
;     ...
;         for (int i = 0; i < 16; ++i) {
;             const int token = 32 * rt + 8 * (i >> 2) + 4 * hl + (i & 3);
;             const float xv = bf2f(xs[token * XS + ch]);
;             const float rr = fast_sigmoid(ga[i] + ba), ii = fast_sigmoid(gi[i] + bi);
;             const float la2 = rr * sp8l2;
;             const float av = __builtin_amdgcn_exp2f(la2);
;             const float t2 = la2 * 1.3862943611f;
;             float em1p = t2 * (1.0f + t2 * (0.5f + t2 * (0.16666667f + t2 * (0.041666668f + t2 * 0.0083333333f)))), em1e = __builtin_fmaf(av, av, -1.0f);
;             asm volatile("" : "+v"(em1p), "+v"(em1e));
;             const float em1 = (t2 > -0.1f) ? em1p : em1e;
;             a[rt][i] = av; u[rt][i] = __builtin_amdgcn_sqrtf(-em1) * (ii * xv);
;         }
	v_lshlrev_b32_e32 v50, 16, v51
	v_mul_f32_e32 v39, v39, v50
	ds_read_u16 v50, v213 offset:2080
	v_add_f32_e32 v51, v189, v56
	v_mul_f32_e32 v51, 0xbfb8aa3b, v51
	v_add_f32_e32 v40, 1.0, v40
	v_exp_f32_e32 v51, v51
	v_rcp_f32_e32 v40, v40
	s_waitcnt lgkmcnt(0)
	v_lshlrev_b32_e32 v50, 16, v50
	v_cmp_lt_f32_e32 vcc, s76, v52
	v_add_f32_e32 v51, 1.0, v51
	v_mul_f32_e32 v40, v40, v50
	v_add_f32_e32 v50, v189, v57
	v_rcp_f32_e32 v51, v51
	v_mul_f32_e32 v50, 0xbfb8aa3b, v50
	v_cndmask_b32_e32 v52, v54, v53, vcc
	v_exp_f32_e32 v50, v50
	v_sqrt_f32_e64 v52, -v52
	v_mul_f32_e32 v51, v193, v51
	v_exp_f32_e32 v200, v51
	v_mul_f32_e32 v51, 0x3fb17218, v51
	v_add_f32_e32 v50, 1.0, v50
	v_mul_f32_e32 v39, v52, v39
	v_fmamk_f32 v52, v51, 0x3c088888, v186
	v_rcp_f32_e32 v50, v50
	v_fmaak_f32 v52, v51, v52, 0x3e2aaaab
	v_add_f32_e32 v41, v190, v41
	v_fma_f32 v52, v51, v52, 0.5
	v_mul_f32_e32 v41, 0xbfb8aa3b, v41
	v_fma_f32 v52, v51, v52, 1.0
	v_exp_f32_e32 v41, v41
	v_mul_f32_e32 v52, v51, v52
	v_fma_f32 v53, v200, v200, -1.0
	v_mul_f32_e32 v50, v193, v50
	v_cmp_lt_f32_e32 vcc, s76, v51
	v_exp_f32_e32 v202, v50
	v_mul_f32_e32 v50, 0x3fb17218, v50
	v_cndmask_b32_e32 v51, v53, v52, vcc
	ds_read_u16 v52, v213 offset:3120
	v_fmamk_f32 v53, v50, 0x3c088888, v186
	v_sqrt_f32_e64 v51, -v51
	v_add_f32_e32 v41, 1.0, v41
	v_fmaak_f32 v53, v50, v53, 0x3e2aaaab
	v_rcp_f32_e32 v41, v41
	v_fma_f32 v53, v50, v53, 0.5
	v_fma_f32 v53, v50, v53, 1.0
	v_mul_f32_e32 v53, v50, v53
	v_fma_f32 v54, v202, v202, -1.0
	v_cmp_lt_f32_e32 vcc, s76, v50
	v_mul_f32_e32 v201, v51, v40
	s_waitcnt lgkmcnt(0)
	v_lshlrev_b32_e32 v40, 16, v52
	v_cndmask_b32_e32 v50, v54, v53, vcc
	v_sqrt_f32_e64 v50, -v50
	v_mul_f32_e32 v40, v41, v40
	v_add_f32_e32 v41, v189, v58
	v_mul_f32_e32 v41, 0xbfb8aa3b, v41
	v_exp_f32_e32 v41, v41
	v_add_f32_e32 v42, v190, v42
	v_mul_f32_e32 v203, v50, v40
	ds_read_u16 v40, v213 offset:8320
	v_mul_f32_e32 v42, 0xbfb8aa3b, v42
	v_exp_f32_e32 v42, v42
	v_add_f32_e32 v41, 1.0, v41
	v_rcp_f32_e32 v41, v41
	s_waitcnt lgkmcnt(0)
	v_lshlrev_b32_e32 v50, 16, v40
	v_add_f32_e32 v40, 1.0, v42
	v_rcp_f32_e32 v42, v40
	v_mul_f32_e32 v41, v193, v41
	v_exp_f32_e32 v40, v41
	v_mul_f32_e32 v41, 0x3fb17218, v41
	v_fmamk_f32 v51, v41, 0x3c088888, v186
	v_fmaak_f32 v51, v41, v51, 0x3e2aaaab
	v_mul_f32_e32 v50, v42, v50
	v_add_f32_e32 v42, v189, v59
	v_fma_f32 v51, v41, v51, 0.5
	v_mul_f32_e32 v42, 0xbfb8aa3b, v42
	v_fma_f32 v51, v41, v51, 1.0
	v_exp_f32_e32 v42, v42
	v_mul_f32_e32 v51, v41, v51
	v_fma_f32 v52, v40, v40, -1.0
	v_cmp_lt_f32_e32 vcc, s76, v41
	v_add_f32_e32 v42, 1.0, v42
	v_rcp_f32_e32 v42, v42
	v_cndmask_b32_e32 v41, v52, v51, vcc
	ds_read_u16 v51, v213 offset:9360
	v_sqrt_f32_e64 v41, -v41
	v_add_f32_e32 v43, v190, v43
	v_mul_f32_e32 v52, v193, v42
	v_mul_f32_e32 v43, 0xbfb8aa3b, v43
	v_mul_f32_e32 v41, v41, v50
	s_waitcnt lgkmcnt(0)
	v_lshlrev_b32_e32 v50, 16, v51
	v_add_f32_e32 v51, v189, v60
	v_mul_f32_e32 v51, 0xbfb8aa3b, v51
	v_exp_f32_e32 v42, v52
	v_mul_f32_e32 v52, 0x3fb17218, v52
	v_exp_f32_e32 v51, v51
	v_exp_f32_e32 v43, v43
	v_fmamk_f32 v53, v52, 0x3c088888, v186
	v_fmaak_f32 v53, v52, v53, 0x3e2aaaab
	v_fma_f32 v53, v52, v53, 0.5
	v_fma_f32 v53, v52, v53, 1.0
	v_add_f32_e32 v51, 1.0, v51
	v_add_f32_e32 v43, 1.0, v43
	v_mul_f32_e32 v53, v52, v53
	v_fma_f32 v54, v42, v42, -1.0
	v_cmp_lt_f32_e32 vcc, s76, v52
	v_rcp_f32_e32 v51, v51
	v_rcp_f32_e32 v43, v43
	v_add_f32_e32 v44, v190, v44
	v_cndmask_b32_e32 v52, v54, v53, vcc
	v_sqrt_f32_e64 v52, -v52
	v_mul_f32_e32 v51, v193, v51
	v_mul_f32_e32 v43, v43, v50
	ds_read_u16 v50, v213 offset:10400
	v_exp_f32_e32 v204, v51
	v_mul_f32_e32 v51, 0x3fb17218, v51
	v_mul_f32_e32 v43, v52, v43
	v_fmamk_f32 v52, v51, 0x3c088888, v186
	v_fmaak_f32 v52, v51, v52, 0x3e2aaaab
	v_mul_f32_e32 v44, 0xbfb8aa3b, v44
	v_fma_f32 v52, v51, v52, 0.5
	v_exp_f32_e32 v44, v44
	v_fma_f32 v52, v51, v52, 1.0
	v_mul_f32_e32 v52, v51, v52
	v_fma_f32 v53, v204, v204, -1.0
	v_cmp_lt_f32_e32 vcc, s76, v51
	v_add_f32_e32 v44, 1.0, v44
	v_rcp_f32_e32 v44, v44
	v_cndmask_b32_e32 v51, v53, v52, vcc
	v_add_f32_e32 v52, v189, v61
	v_mul_f32_e32 v52, 0xbfb8aa3b, v52
	v_exp_f32_e32 v52, v52
	s_waitcnt lgkmcnt(0)
	ds_read_u16 v53, v213 offset:11440
	ds_read_u16 v70, v213 offset:16640
	v_lshlrev_b32_e32 v50, 16, v50
	v_mul_f32_e32 v50, v44, v50
	v_add_f32_e32 v45, v190, v45
	v_add_f32_e32 v44, 1.0, v52
	v_rcp_f32_e32 v44, v44
	v_mul_f32_e32 v45, 0xbfb8aa3b, v45
	v_exp_f32_e32 v52, v45
	v_add_f32_e32 v45, v189, v62
	v_mul_f32_e32 v44, v193, v44
	v_mul_f32_e32 v54, 0x3fb17218, v44
	v_mul_f32_e32 v45, 0xbfb8aa3b, v45
	v_exp_f32_e32 v205, v44
	v_fmamk_f32 v44, v54, 0x3c088888, v186
	v_exp_f32_e32 v45, v45
	v_fmaak_f32 v44, v54, v44, 0x3e2aaaab
	v_fma_f32 v44, v54, v44, 0.5
	v_fma_f32 v44, v54, v44, 1.0
	v_mul_f32_e32 v55, v54, v44
	v_add_f32_e32 v44, 1.0, v45
	v_rcp_f32_e32 v44, v44
	v_add_f32_e32 v57, v189, v63
	v_mul_f32_e32 v57, 0xbfb8aa3b, v57
	v_exp_f32_e32 v57, v57
	v_mul_f32_e32 v45, v193, v44
	v_mul_f32_e32 v154, 0x3fb17218, v45
	v_exp_f32_e32 v44, v45
	v_fmamk_f32 v45, v154, 0x3c088888, v186
	v_fmaak_f32 v45, v154, v45, 0x3e2aaaab
	v_fma_f32 v45, v154, v45, 0.5
	v_fma_f32 v45, v154, v45, 1.0
	v_mul_f32_e32 v155, v154, v45
	v_add_f32_e32 v45, 1.0, v57
	v_rcp_f32_e32 v45, v45
	v_add_f32_e32 v58, v189, v64
	v_mul_f32_e32 v58, 0xbfb8aa3b, v58
	v_exp_f32_e32 v58, v58
	v_mul_f32_e32 v57, v193, v45
	v_mul_f32_e32 v159, 0x3fb17218, v57
	v_exp_f32_e32 v45, v57
	v_fmamk_f32 v57, v159, 0x3c088888, v186
	v_fmaak_f32 v57, v159, v57, 0x3e2aaaab
	v_fma_f32 v57, v159, v57, 0.5
	v_fma_f32 v57, v159, v57, 1.0
	v_mul_f32_e32 v209, v159, v57
	v_add_f32_e32 v57, 1.0, v58
	v_rcp_f32_e32 v57, v57
	v_add_f32_e32 v58, v189, v65
	v_mul_f32_e32 v58, 0xbfb8aa3b, v58
	v_exp_f32_e32 v58, v58
	v_mul_f32_e32 v57, v193, v57
	v_mul_f32_e32 v222, 0x3fb17218, v57
	v_exp_f32_e32 v206, v57
	v_fmamk_f32 v57, v222, 0x3c088888, v186
	v_fmaak_f32 v57, v222, v57, 0x3e2aaaab
	v_fma_f32 v57, v222, v57, 0.5
	v_fma_f32 v57, v222, v57, 1.0
	v_mul_f32_e32 v223, v222, v57
	v_add_f32_e32 v57, 1.0, v58
	v_rcp_f32_e32 v57, v57
	v_sqrt_f32_e64 v51, -v51
	v_fma_f32 v56, v205, v205, -1.0
	v_fma_f32 v156, v44, v44, -1.0
	v_mul_f32_e32 v57, v193, v57
	v_mul_f32_e32 v226, 0x3fb17218, v57
	v_exp_f32_e32 v207, v57
	v_fmamk_f32 v57, v226, 0x3c088888, v186
	v_fmaak_f32 v57, v226, v57, 0x3e2aaaab
	v_fma_f32 v57, v226, v57, 0.5
	v_fma_f32 v57, v226, v57, 1.0
	v_fma_f32 v210, v45, v45, -1.0
	v_fma_f32 v224, v206, v206, -1.0
	v_mul_f32_e32 v227, v226, v57
	v_fma_f32 v228, v207, v207, -1.0
	ds_read_u16 v158, v213 offset:17680
	ds_read_u16 v212, v213 offset:18720
	ds_read_u16 v225, v213 offset:19760
	ds_read_b128 v[66:69], v187 offset:33280
	ds_read_b128 v[214:217], v187 offset:33312
	v_mul_f32_e32 v208, v51, v50
	v_add_f32_e32 v50, 1.0, v52
	v_cmp_lt_f32_e32 vcc, s76, v54
	v_rcp_f32_e32 v72, v50
	s_waitcnt lgkmcnt(6)
; __device__ __forceinline__ float bf2f(bf16_t b) { return __uint_as_float(((unsigned)b) << 16); }
; __device__ __forceinline__ float fast_sigmoid(float x) { return __builtin_amdgcn_rcpf(1.0f + __builtin_amdgcn_exp2f(-1.4426950408889634f * x)); }
; template <int DIR>
; __device__ __forceinline__ void scan_dir(PP p, const bf16_t* xs, const ScanW& w, ScanW& wn, int ndir, int nct, bool do_next, int n, int ct, int l31, int hl, int id, int rowbase, bool latent, float (&hf)[2][16]) {
;     ...
;     for (int rt = 0; rt < 2; ++rt) {
;         bf16x8 af[4];
; #pragma unroll
;         for (int st = 0; st < 4; ++st) af[st] = *(const bf16x8*)(xs + (32 * rt + l31) * XS + 64 * n + 16 * st + 8 * hl);
;         f32x16 ga, gi;
; #pragma unroll
;         for (int i = 0; i < 16; ++i) { ga[i] = 0.f; gi[i] = 0.f; }
; #pragma unroll
;         for (int st = 0; st < 4; ++st) { ga = __builtin_amdgcn_mfma_f32_32x32x16_bf16(af[st], wfa[st], ga, 0, 0, 0); gi = __builtin_amdgcn_mfma_f32_32x32x16_bf16(af[st], wfi[st], gi, 0, 0, 0); }
; #pragma unroll
;         for (int i = 0; i < 16; ++i) {
;             const int token = 32 * rt + 8 * (i >> 2) + 4 * hl + (i & 3);
;             const float xv = bf2f(xs[token * XS + ch]);
;             const float rr = fast_sigmoid(ga[i] + ba), ii = fast_sigmoid(gi[i] + bi);
;             const float la2 = rr * sp8l2;
;             const float av = __builtin_amdgcn_exp2f(la2);
;             const float t2 = la2 * 1.3862943611f;
;             float em1p = t2 * (1.0f + t2 * (0.5f + t2 * (0.16666667f + t2 * (0.041666668f + t2 * 0.0083333333f)))), em1e = __builtin_fmaf(av, av, -1.0f);
;             asm volatile("" : "+v"(em1p), "+v"(em1e));
;             const float em1 = (t2 > -0.1f) ? em1p : em1e;
;             a[rt][i] = av; u[rt][i] = __builtin_amdgcn_sqrtf(-em1) * (ii * xv);
;         }
	v_lshlrev_b32_e32 v71, 16, v53
	v_cndmask_b32_e32 v50, v56, v55, vcc
	v_sqrt_f32_e64 v73, -v50
	v_mul_f32_e32 v71, v72, v71
	s_waitcnt lgkmcnt(1)
	v_mfma_f32_32x32x16_bf16 v[50:65], v[66:69], v[82:85], 0
	v_lshlrev_b32_e32 v230, 16, v70
	v_mul_f32_e32 v211, v73, v71
	v_add_f32_e32 v46, v190, v46
	v_mul_f32_e32 v46, 0xbfb8aa3b, v46
	v_exp_f32_e32 v46, v46
	ds_read_b128 v[218:221], v187 offset:33344
	v_cmp_lt_f32_e32 vcc, s76, v154
	v_mfma_f32_32x32x16_bf16 v[66:81], v[66:69], v[98:101], 0
	v_add_f32_e32 v46, 1.0, v46
	v_add_f32_e32 v47, v190, v47
	v_rcp_f32_e32 v46, v46
	v_cndmask_b32_e32 v154, v156, v155, vcc
	v_mul_f32_e32 v47, 0xbfb8aa3b, v47
	v_sqrt_f32_e64 v154, -v154
	v_exp_f32_e32 v155, v47
	s_waitcnt lgkmcnt(1)
	v_mfma_f32_32x32x16_bf16 v[66:81], v[214:217], v[94:97], v[66:81]
	v_mul_f32_e32 v46, v46, v230
	v_mul_f32_e32 v47, v154, v46
	v_add_f32_e32 v154, 1.0, v155
	v_rcp_f32_e32 v154, v154
	v_add_f32_e32 v48, v190, v48
	v_lshlrev_b32_e32 v46, 16, v158
	v_cmp_lt_f32_e32 vcc, s76, v159
	v_mfma_f32_32x32x16_bf16 v[50:65], v[214:217], v[86:89], v[50:65]
	ds_read_b128 v[214:217], v187 offset:33376
	v_mul_f32_e32 v48, 0xbfb8aa3b, v48
	v_cndmask_b32_e32 v155, v210, v209, vcc
	v_mul_f32_e32 v46, v154, v46
	v_exp_f32_e32 v154, v48
	v_add_f32_e32 v49, v190, v49
	v_sqrt_f32_e64 v155, -v155
	s_waitcnt lgkmcnt(1)
	v_mfma_f32_32x32x16_bf16 v[66:81], v[218:221], v[102:105], v[66:81]
	v_mul_f32_e32 v49, 0xbfb8aa3b, v49
	v_exp_f32_e32 v49, v49
	v_add_f32_e32 v154, 1.0, v154
	v_cmp_lt_f32_e32 vcc, s76, v222
	v_mul_f32_e32 v48, v155, v46
	v_rcp_f32_e32 v154, v154
	v_cndmask_b32_e32 v155, v224, v223, vcc
	v_mfma_f32_32x32x16_bf16 v[50:65], v[218:221], v[90:93], v[50:65]
	v_sqrt_f32_e64 v155, -v155
	v_add_f32_e32 v49, 1.0, v49
	v_rcp_f32_e32 v49, v49
	v_lshlrev_b32_e32 v46, 16, v212
	v_cmp_lt_f32_e32 vcc, s76, v226
	v_mul_f32_e32 v46, v154, v46
	v_mul_f32_e32 v209, v155, v46
	s_waitcnt lgkmcnt(0)
	ds_read_u16 v229, v213 offset:24960
	v_mfma_f32_32x32x16_bf16 v[66:81], v[214:217], v[110:113], v[66:81]
	v_cndmask_b32_e32 v154, v228, v227, vcc
	v_sqrt_f32_e64 v154, -v154
	v_lshlrev_b32_e32 v46, 16, v225
	v_mul_f32_e32 v46, v49, v46
	v_mul_f32_e32 v210, v154, v46
	v_mul_f32_e32 v158, v205, v204
	v_mfma_f32_32x32x16_bf16 v[50:65], v[214:217], v[106:109], v[50:65]
	s_nop 3
	v_add_f32_e32 v49, v190, v66
	v_mul_f32_e32 v49, 0xbfb8aa3b, v49
	v_exp_f32_e32 v49, v49
	v_mul_f32_e32 v158, v42, v158
	v_mul_f32_e32 v217, v40, v158
	v_mul_f32_e32 v158, v207, v206
	v_add_f32_e32 v49, 1.0, v49
	s_nop 0
	v_add_f32_e32 v46, v189, v50
	v_mul_f32_e32 v46, 0xbfb8aa3b, v46
	v_exp_f32_e32 v46, v46
	v_rcp_f32_e32 v49, v49
	s_waitcnt lgkmcnt(0)
	v_lshlrev_b32_e32 v50, 16, v229
	v_add_f32_e32 v52, v189, v52
	v_add_f32_e32 v46, 1.0, v46
	v_rcp_f32_e32 v46, v46
	v_mul_f32_e32 v49, v49, v50
	v_add_f32_e32 v50, v189, v51
	v_mul_f32_e32 v50, 0xbfb8aa3b, v50
	v_exp_f32_e32 v50, v50
	v_mul_f32_e32 v66, v193, v46
	v_exp_f32_e32 v46, v66
	v_mul_f32_e32 v66, 0x3fb17218, v66
	v_fmamk_f32 v154, v66, 0x3c088888, v186
	v_fmaak_f32 v154, v66, v154, 0x3e2aaaab
	v_add_f32_e32 v50, 1.0, v50
	v_fma_f32 v154, v66, v154, 0.5
	v_add_f32_e32 v51, v190, v67
	ds_read_u16 v67, v213 offset:26000
	v_rcp_f32_e32 v50, v50
	v_fma_f32 v154, v66, v154, 1.0
	v_mul_f32_e32 v51, 0xbfb8aa3b, v51
	v_mul_f32_e32 v154, v66, v154
	v_fma_f32 v155, v46, v46, -1.0
	v_exp_f32_e32 v51, v51
	v_cmp_lt_f32_e32 vcc, s76, v66
	v_add_f32_e32 v51, 1.0, v51
	v_cndmask_b32_e32 v66, v155, v154, vcc
	v_mul_f32_e32 v154, v193, v50
	v_exp_f32_e32 v50, v154
	v_mul_f32_e32 v154, 0x3fb17218, v154
	v_sqrt_f32_e64 v66, -v66
	v_fmamk_f32 v155, v154, 0x3c088888, v186
	v_rcp_f32_e32 v51, v51
	v_fmaak_f32 v155, v154, v155, 0x3e2aaaab
	v_fma_f32 v155, v154, v155, 0.5
	v_fma_f32 v155, v154, v155, 1.0
	v_mul_f32_e32 v155, v154, v155
	v_fma_f32 v156, v50, v50, -1.0
	v_mul_f32_e32 v49, v49, v66
	s_waitcnt lgkmcnt(0)
	v_lshlrev_b32_e32 v66, 16, v67
	v_mul_f32_e32 v52, 0xbfb8aa3b, v52
	v_add_f32_e32 v67, v190, v68
	v_mul_f32_e32 v51, v51, v66
	ds_read_u16 v66, v213 offset:27040
	v_exp_f32_e32 v52, v52
	v_mul_f32_e32 v67, 0xbfb8aa3b, v67
	v_exp_f32_e32 v67, v67
	v_cmp_lt_f32_e32 vcc, s76, v154
	v_add_f32_e32 v52, 1.0, v52
	v_rcp_f32_e32 v52, v52
	s_waitcnt lgkmcnt(0)
	v_lshlrev_b32_e32 v68, 16, v66
	v_add_f32_e32 v66, 1.0, v67
	v_add_f32_e32 v53, v189, v53
	v_cndmask_b32_e32 v154, v156, v155, vcc
	v_rcp_f32_e32 v67, v66
	v_mul_f32_e32 v53, 0xbfb8aa3b, v53
	v_sqrt_f32_e64 v154, -v154
	v_exp_f32_e32 v53, v53
	v_mul_f32_e32 v52, v193, v52
	v_exp_f32_e32 v66, v52
	v_mul_f32_e32 v52, 0x3fb17218, v52
	v_mul_f32_e32 v67, v67, v68
	v_add_f32_e32 v68, v190, v69
	ds_read_u16 v69, v213 offset:28080
	v_mul_f32_e32 v51, v51, v154
	v_fmamk_f32 v154, v52, 0x3c088888, v186
	v_mul_f32_e32 v68, 0xbfb8aa3b, v68
	v_add_f32_e32 v53, 1.0, v53
	v_fmaak_f32 v154, v52, v154, 0x3e2aaaab
	v_exp_f32_e32 v68, v68
	v_rcp_f32_e32 v53, v53
	v_fma_f32 v154, v52, v154, 0.5
	v_fma_f32 v154, v52, v154, 1.0
	v_mul_f32_e32 v154, v52, v154
	v_fma_f32 v155, v66, v66, -1.0
	v_cmp_lt_f32_e32 vcc, s76, v52
	v_add_f32_e32 v68, 1.0, v68
	v_mul_f32_e32 v53, v193, v53
	v_cndmask_b32_e32 v52, v155, v154, vcc
	v_rcp_f32_e32 v154, v68
	v_exp_f32_e32 v68, v53
	v_mul_f32_e32 v53, 0x3fb17218, v53
	v_fmamk_f32 v155, v53, 0x3c088888, v186
	v_fmaak_f32 v155, v53, v155, 0x3e2aaaab
	v_fma_f32 v155, v53, v155, 0.5
	v_fma_f32 v155, v53, v155, 1.0
	v_sqrt_f32_e64 v52, -v52
	v_mul_f32_e32 v155, v53, v155
	v_fma_f32 v156, v68, v68, -1.0
	v_cmp_lt_f32_e32 vcc, s76, v53
	v_mul_f32_e32 v67, v67, v52
	s_waitcnt lgkmcnt(0)
; __device__ __forceinline__ float bf2f(bf16_t b) { return __uint_as_float(((unsigned)b) << 16); }
; __device__ __forceinline__ float fast_sigmoid(float x) { return __builtin_amdgcn_rcpf(1.0f + __builtin_amdgcn_exp2f(-1.4426950408889634f * x)); }
; template <int DIR>
; __device__ __forceinline__ void scan_dir(PP p, const bf16_t* xs, const ScanW& w, ScanW& wn, int ndir, int nct, bool do_next, int n, int ct, int l31, int hl, int id, int rowbase, bool latent, float (&hf)[2][16]) {
;     ...
;         for (int i = 0; i < 16; ++i) {
;             const int token = 32 * rt + 8 * (i >> 2) + 4 * hl + (i & 3);
;             const float xv = bf2f(xs[token * XS + ch]);
;             const float rr = fast_sigmoid(ga[i] + ba), ii = fast_sigmoid(gi[i] + bi);
;             const float la2 = rr * sp8l2;
;             const float av = __builtin_amdgcn_exp2f(la2);
;             const float t2 = la2 * 1.3862943611f;
;             float em1p = t2 * (1.0f + t2 * (0.5f + t2 * (0.16666667f + t2 * (0.041666668f + t2 * 0.0083333333f)))), em1e = __builtin_fmaf(av, av, -1.0f);
;             asm volatile("" : "+v"(em1p), "+v"(em1e));
;             const float em1 = (t2 > -0.1f) ? em1p : em1e;
;             a[rt][i] = av; u[rt][i] = __builtin_amdgcn_sqrtf(-em1) * (ii * xv);
;         }
	v_lshlrev_b32_e32 v52, 16, v69
	v_cndmask_b32_e32 v53, v156, v155, vcc
	v_sqrt_f32_e64 v53, -v53
	v_mul_f32_e32 v52, v154, v52
	v_add_f32_e32 v56, v189, v56
	v_mul_f32_e32 v56, 0xbfb8aa3b, v56
	v_mul_f32_e32 v69, v53, v52
	ds_read_u16 v52, v0 offset:41600
	v_add_f32_e32 v53, v189, v54
	v_add_f32_e32 v54, v190, v70
	v_mul_f32_e32 v54, 0xbfb8aa3b, v54
	v_exp_f32_e32 v54, v54
	v_mul_f32_e32 v53, 0xbfb8aa3b, v53
	v_exp_f32_e32 v53, v53
	s_waitcnt lgkmcnt(0)
	v_lshlrev_b32_e32 v70, 16, v52
	v_add_f32_e32 v52, 1.0, v54
	v_rcp_f32_e32 v54, v52
	v_add_f32_e32 v53, 1.0, v53
	v_rcp_f32_e32 v53, v53
	v_exp_f32_e32 v56, v56
	v_mul_f32_e32 v70, v54, v70
	v_add_f32_e32 v54, v189, v55
	v_mul_f32_e32 v54, 0xbfb8aa3b, v54
	v_exp_f32_e32 v54, v54
	v_mul_f32_e32 v53, v193, v53
	v_exp_f32_e32 v52, v53
	v_mul_f32_e32 v53, 0x3fb17218, v53
	v_fmamk_f32 v154, v53, 0x3c088888, v186
	v_fmaak_f32 v154, v53, v154, 0x3e2aaaab
	v_add_f32_e32 v54, 1.0, v54
	v_fma_f32 v154, v53, v154, 0.5
	v_add_f32_e32 v55, v190, v71
	ds_read_u16 v71, v0 offset:42640
	v_rcp_f32_e32 v54, v54
	v_fma_f32 v154, v53, v154, 1.0
	v_mul_f32_e32 v55, 0xbfb8aa3b, v55
	v_mul_f32_e32 v154, v53, v154
	v_fma_f32 v155, v52, v52, -1.0
	v_exp_f32_e32 v55, v55
	v_cmp_lt_f32_e32 vcc, s76, v53
	v_add_f32_e32 v55, 1.0, v55
	v_cndmask_b32_e32 v53, v155, v154, vcc
	v_mul_f32_e32 v154, v193, v54
	v_exp_f32_e32 v54, v154
	v_mul_f32_e32 v154, 0x3fb17218, v154
	v_sqrt_f32_e64 v53, -v53
	v_fmamk_f32 v155, v154, 0x3c088888, v186
	v_rcp_f32_e32 v55, v55
	v_fmaak_f32 v155, v154, v155, 0x3e2aaaab
	v_fma_f32 v155, v154, v155, 0.5
	v_fma_f32 v155, v154, v155, 1.0
	v_mul_f32_e32 v155, v154, v155
	v_fma_f32 v156, v54, v54, -1.0
	v_mul_f32_e32 v53, v53, v70
	s_waitcnt lgkmcnt(0)
	v_lshlrev_b32_e32 v70, 16, v71
	v_add_f32_e32 v71, v190, v72
	v_mul_f32_e32 v55, v55, v70
	ds_read_u16 v70, v0 offset:43680
	v_mul_f32_e32 v71, 0xbfb8aa3b, v71
	v_exp_f32_e32 v71, v71
	v_add_f32_e32 v56, 1.0, v56
	v_cmp_lt_f32_e32 vcc, s76, v154
	v_rcp_f32_e32 v56, v56
	s_waitcnt lgkmcnt(0)
	v_lshlrev_b32_e32 v72, 16, v70
	v_add_f32_e32 v70, 1.0, v71
	v_add_f32_e32 v57, v189, v57
	v_cndmask_b32_e32 v154, v156, v155, vcc
	v_rcp_f32_e32 v71, v70
	v_mul_f32_e32 v57, 0xbfb8aa3b, v57
	v_sqrt_f32_e64 v154, -v154
	v_exp_f32_e32 v57, v57
	v_mul_f32_e32 v56, v193, v56
	v_exp_f32_e32 v70, v56
	v_mul_f32_e32 v56, 0x3fb17218, v56
	v_mul_f32_e32 v71, v71, v72
	v_add_f32_e32 v72, v190, v73
	ds_read_u16 v73, v0 offset:44720
	v_mul_f32_e32 v55, v154, v55
	v_fmamk_f32 v154, v56, 0x3c088888, v186
	v_mul_f32_e32 v72, 0xbfb8aa3b, v72
	v_add_f32_e32 v57, 1.0, v57
	v_fmaak_f32 v154, v56, v154, 0x3e2aaaab
	v_exp_f32_e32 v72, v72
	v_rcp_f32_e32 v57, v57
	v_fma_f32 v154, v56, v154, 0.5
	v_fma_f32 v154, v56, v154, 1.0
	v_mul_f32_e32 v154, v56, v154
	v_fma_f32 v155, v70, v70, -1.0
	v_cmp_lt_f32_e32 vcc, s76, v56
	v_add_f32_e32 v72, 1.0, v72
	v_mul_f32_e32 v57, v193, v57
	v_cndmask_b32_e32 v56, v155, v154, vcc
	v_rcp_f32_e32 v154, v72
	v_exp_f32_e32 v72, v57
	v_mul_f32_e32 v57, 0x3fb17218, v57
	v_fmamk_f32 v155, v57, 0x3c088888, v186
	v_fmaak_f32 v155, v57, v155, 0x3e2aaaab
	v_fma_f32 v155, v57, v155, 0.5
	v_fma_f32 v155, v57, v155, 1.0
	v_sqrt_f32_e64 v56, -v56
	v_mul_f32_e32 v155, v57, v155
	v_fma_f32 v156, v72, v72, -1.0
	v_cmp_lt_f32_e32 vcc, s76, v57
	v_mul_f32_e32 v71, v56, v71
	s_waitcnt lgkmcnt(0)
	v_lshlrev_b32_e32 v56, 16, v73
	v_cndmask_b32_e32 v57, v156, v155, vcc
	v_sqrt_f32_e64 v57, -v57
	v_mul_f32_e32 v56, v154, v56
	v_add_f32_e32 v60, v189, v60
	v_mul_f32_e32 v60, 0xbfb8aa3b, v60
	v_mul_f32_e32 v73, v57, v56
	ds_read_u16 v56, v0 offset:49920
	v_add_f32_e32 v57, v189, v58
	v_add_f32_e32 v58, v190, v74
	v_mul_f32_e32 v58, 0xbfb8aa3b, v58
	v_exp_f32_e32 v58, v58
	v_mul_f32_e32 v57, 0xbfb8aa3b, v57
	v_exp_f32_e32 v57, v57
	s_waitcnt lgkmcnt(0)
	v_lshlrev_b32_e32 v74, 16, v56
	v_add_f32_e32 v56, 1.0, v58
	v_rcp_f32_e32 v58, v56
	v_add_f32_e32 v57, 1.0, v57
	v_rcp_f32_e32 v57, v57
	v_exp_f32_e32 v60, v60
	v_mul_f32_e32 v74, v58, v74
	v_add_f32_e32 v58, v189, v59
	v_mul_f32_e32 v58, 0xbfb8aa3b, v58
	v_exp_f32_e32 v58, v58
	v_mul_f32_e32 v57, v193, v57
	v_exp_f32_e32 v56, v57
	v_mul_f32_e32 v57, 0x3fb17218, v57
	v_fmamk_f32 v154, v57, 0x3c088888, v186
	v_fmaak_f32 v154, v57, v154, 0x3e2aaaab
	v_add_f32_e32 v58, 1.0, v58
	v_fma_f32 v154, v57, v154, 0.5
	v_add_f32_e32 v59, v190, v75
	ds_read_u16 v75, v0 offset:50960
	v_rcp_f32_e32 v58, v58
	v_fma_f32 v154, v57, v154, 1.0
	v_mul_f32_e32 v59, 0xbfb8aa3b, v59
	v_mul_f32_e32 v154, v57, v154
	v_fma_f32 v155, v56, v56, -1.0
	v_exp_f32_e32 v59, v59
	v_cmp_lt_f32_e32 vcc, s76, v57
	v_add_f32_e32 v59, 1.0, v59
	v_cndmask_b32_e32 v57, v155, v154, vcc
	v_mul_f32_e32 v154, v193, v58
	v_exp_f32_e32 v58, v154
	v_mul_f32_e32 v154, 0x3fb17218, v154
	v_sqrt_f32_e64 v57, -v57
	v_fmamk_f32 v155, v154, 0x3c088888, v186
	v_rcp_f32_e32 v59, v59
	v_fmaak_f32 v155, v154, v155, 0x3e2aaaab
	v_fma_f32 v155, v154, v155, 0.5
	v_fma_f32 v155, v154, v155, 1.0
	v_mul_f32_e32 v155, v154, v155
	v_fma_f32 v156, v58, v58, -1.0
	v_mul_f32_e32 v57, v57, v74
	s_waitcnt lgkmcnt(0)
	v_lshlrev_b32_e32 v74, 16, v75
	v_add_f32_e32 v75, v190, v76
	v_mul_f32_e32 v59, v59, v74
	ds_read_u16 v74, v0 offset:52000
	v_mul_f32_e32 v75, 0xbfb8aa3b, v75
	v_exp_f32_e32 v75, v75
	v_add_f32_e32 v60, 1.0, v60
	v_cmp_lt_f32_e32 vcc, s76, v154
	v_rcp_f32_e32 v60, v60
	s_waitcnt lgkmcnt(0)
; __device__ __forceinline__ float bf2f(bf16_t b) { return __uint_as_float(((unsigned)b) << 16); }
; __device__ __forceinline__ float fast_sigmoid(float x) { return __builtin_amdgcn_rcpf(1.0f + __builtin_amdgcn_exp2f(-1.4426950408889634f * x)); }
; template <int DIR>
; __device__ __forceinline__ void scan_dir(PP p, const bf16_t* xs, const ScanW& w, ScanW& wn, int ndir, int nct, bool do_next, int n, int ct, int l31, int hl, int id, int rowbase, bool latent, float (&hf)[2][16]) {
;     ...
;         for (int i = 0; i < 16; ++i) {
;             const int token = 32 * rt + 8 * (i >> 2) + 4 * hl + (i & 3);
;             const float xv = bf2f(xs[token * XS + ch]);
;             const float rr = fast_sigmoid(ga[i] + ba), ii = fast_sigmoid(gi[i] + bi);
;             const float la2 = rr * sp8l2;
;             const float av = __builtin_amdgcn_exp2f(la2);
;             const float t2 = la2 * 1.3862943611f;
;             float em1p = t2 * (1.0f + t2 * (0.5f + t2 * (0.16666667f + t2 * (0.041666668f + t2 * 0.0083333333f)))), em1e = __builtin_fmaf(av, av, -1.0f);
;             asm volatile("" : "+v"(em1p), "+v"(em1e));
;             const float em1 = (t2 > -0.1f) ? em1p : em1e;
;             a[rt][i] = av; u[rt][i] = __builtin_amdgcn_sqrtf(-em1) * (ii * xv);
;         }
	v_lshlrev_b32_e32 v76, 16, v74
	v_add_f32_e32 v74, 1.0, v75
	v_add_f32_e32 v61, v189, v61
	v_cndmask_b32_e32 v154, v156, v155, vcc
	v_rcp_f32_e32 v75, v74
	v_mul_f32_e32 v61, 0xbfb8aa3b, v61
	v_sqrt_f32_e64 v154, -v154
	v_exp_f32_e32 v61, v61
	v_mul_f32_e32 v60, v193, v60
	v_exp_f32_e32 v74, v60
	v_mul_f32_e32 v60, 0x3fb17218, v60
	v_mul_f32_e32 v75, v75, v76
	v_add_f32_e32 v76, v190, v77
	ds_read_u16 v77, v0 offset:53040
	v_mul_f32_e32 v59, v154, v59
	v_fmamk_f32 v154, v60, 0x3c088888, v186
	v_mul_f32_e32 v76, 0xbfb8aa3b, v76
	v_add_f32_e32 v61, 1.0, v61
	v_fmaak_f32 v154, v60, v154, 0x3e2aaaab
	v_exp_f32_e32 v76, v76
	v_rcp_f32_e32 v61, v61
	v_fma_f32 v154, v60, v154, 0.5
	v_fma_f32 v154, v60, v154, 1.0
	v_mul_f32_e32 v154, v60, v154
	v_fma_f32 v155, v74, v74, -1.0
	v_cmp_lt_f32_e32 vcc, s76, v60
	v_add_f32_e32 v76, 1.0, v76
	v_mul_f32_e32 v61, v193, v61
	v_cndmask_b32_e32 v60, v155, v154, vcc
	v_rcp_f32_e32 v154, v76
	v_exp_f32_e32 v76, v61
	v_mul_f32_e32 v61, 0x3fb17218, v61
	v_fmamk_f32 v155, v61, 0x3c088888, v186
	v_fmaak_f32 v155, v61, v155, 0x3e2aaaab
	v_fma_f32 v155, v61, v155, 0.5
	v_fma_f32 v155, v61, v155, 1.0
	v_sqrt_f32_e64 v60, -v60
	v_mul_f32_e32 v155, v61, v155
	v_fma_f32 v156, v76, v76, -1.0
	v_cmp_lt_f32_e32 vcc, s76, v61
	v_mul_f32_e32 v75, v60, v75
	s_waitcnt lgkmcnt(0)
	v_lshlrev_b32_e32 v60, 16, v77
	v_cndmask_b32_e32 v61, v156, v155, vcc
	v_sqrt_f32_e64 v61, -v61
	v_mul_f32_e32 v60, v154, v60
	v_add_f32_e32 v64, v189, v64
	v_mul_f32_e32 v64, 0xbfb8aa3b, v64
	v_mul_f32_e32 v77, v61, v60
	ds_read_u16 v60, v0 offset:58240
	v_add_f32_e32 v61, v189, v62
	v_add_f32_e32 v62, v190, v78
	v_mul_f32_e32 v62, 0xbfb8aa3b, v62
	v_mul_f32_e32 v61, 0xbfb8aa3b, v61
	v_exp_f32_e32 v62, v62
	v_exp_f32_e32 v61, v61
	s_waitcnt lgkmcnt(0)
	v_lshlrev_b32_e32 v78, 16, v60
	v_exp_f32_e32 v64, v64
	v_add_f32_e32 v60, 1.0, v62
	v_add_f32_e32 v61, 1.0, v61
	v_rcp_f32_e32 v62, v60
	v_rcp_f32_e32 v61, v61
	v_add_f32_e32 v65, v189, v65
	v_mul_f32_e32 v65, 0xbfb8aa3b, v65
	v_mul_f32_e32 v78, v62, v78
	v_add_f32_e32 v62, v189, v63
	v_mul_f32_e32 v61, v193, v61
	v_mul_f32_e32 v62, 0xbfb8aa3b, v62
	v_exp_f32_e32 v60, v61
	v_mul_f32_e32 v61, 0x3fb17218, v61
	v_exp_f32_e32 v62, v62
	v_fmamk_f32 v154, v61, 0x3c088888, v186
	v_fmaak_f32 v154, v61, v154, 0x3e2aaaab
	v_fma_f32 v154, v61, v154, 0.5
	v_fma_f32 v154, v61, v154, 1.0
	v_add_f32_e32 v62, 1.0, v62
	v_mul_f32_e32 v154, v61, v154
	v_fma_f32 v155, v60, v60, -1.0
	v_cmp_lt_f32_e32 vcc, s76, v61
	v_add_f32_e32 v63, v190, v79
	ds_read_u16 v79, v0 offset:59280
	v_rcp_f32_e32 v62, v62
	v_mul_f32_e32 v63, 0xbfb8aa3b, v63
	v_cndmask_b32_e32 v61, v155, v154, vcc
	v_sqrt_f32_e64 v61, -v61
	v_exp_f32_e32 v63, v63
	v_mul_f32_e32 v154, v193, v62
	v_exp_f32_e32 v62, v154
	v_mul_f32_e32 v154, 0x3fb17218, v154
	v_add_f32_e32 v63, 1.0, v63
	v_fmamk_f32 v155, v154, 0x3c088888, v186
	v_mul_f32_e32 v61, v61, v78
	s_waitcnt lgkmcnt(0)
	v_lshlrev_b32_e32 v78, 16, v79
	v_add_f32_e32 v79, v190, v80
	v_rcp_f32_e32 v63, v63
	v_fmaak_f32 v155, v154, v155, 0x3e2aaaab
	v_mul_f32_e32 v79, 0xbfb8aa3b, v79
	v_fma_f32 v155, v154, v155, 0.5
	v_exp_f32_e32 v79, v79
	v_exp_f32_e32 v65, v65
	v_fma_f32 v155, v154, v155, 1.0
	v_mul_f32_e32 v155, v154, v155
	v_fma_f32 v156, v62, v62, -1.0
	v_add_f32_e32 v64, 1.0, v64
	v_cmp_lt_f32_e32 vcc, s76, v154
	v_mul_f32_e32 v63, v63, v78
	ds_read_u16 v78, v0 offset:60320
	v_rcp_f32_e32 v64, v64
	v_cndmask_b32_e32 v154, v156, v155, vcc
	v_add_f32_e32 v79, 1.0, v79
	v_add_f32_e32 v65, 1.0, v65
	v_sqrt_f32_e64 v154, -v154
	v_rcp_f32_e32 v79, v79
	v_rcp_f32_e32 v65, v65
	v_mul_f32_e32 v80, v193, v64
	s_waitcnt lgkmcnt(0)
; __device__ __forceinline__ void scan_loadw(PP p, int dir, int n, int ct, int l31, int hl, ScanW& w) {
;     unsigned chv = (unsigned)(32 * ct + l31); asm volatile("" : "+v"(chv));
;     const unsigned ch = (unsigned)(dir * 512 + 64 * n) + chv;
;     w.ba = p->lru_b_a[ch]; w.bi = p->lru_b_i[ch];
;     w.sp8l2 = ((const float*)(p->ws + WS_SP8))[ch] * 1.4426950408889634f;
;     const bf16_t* wa_b = (const bf16_t*)(p->ws + WS_LRU) + (size_t)((dir * 2 + 0) * 8 + n) * 4096;
;     const bf16_t* wi_b = (const bf16_t*)(p->ws + WS_LRU) + (size_t)((dir * 2 + 1) * 8 + n) * 4096;
;     const unsigned lo = chv * 64u + 8u * (unsigned)hl;
; #pragma unroll
;     for (int st = 0; st < 4; ++st) { w.wfa[st] = *(const bf16x8*)(wa_b + lo + 16 * st); w.wfi[st] = *(const bf16x8*)(wi_b + lo + 16 * st); }
; }
; template <int DIR>
; __device__ __forceinline__ void scan_dir(PP p, const bf16_t* xs, const ScanW& w, ScanW& wn, int ndir, int nct, bool do_next, int n, int ct, int l31, int hl, int id, int rowbase, bool latent, float (&hf)[2][16]) {
;     ...
; #pragma unroll
;     for (int k = 0; k < 8; ++k) {
;         const int rt = k >> 2, g = k & 3;
;         float H = 0.f, A = 1.f;
; #pragma unroll
;         for (int jj = 0; jj < 4; ++jj) { const int j = DIR ? 3 - jj : jj; const float av = a[rt][4 * g + j]; H = av * H + u[rt][4 * g + j]; A *= av; }
;         Ao[k] = A; Ho[k] = H; Ap[k] = __shfl_xor(A, 32); Hp[k] = __shfl_xor(H, 32);
;     }
	v_lshlrev_b32_e32 v78, 16, v78
	v_exp_f32_e32 v64, v80
	v_mul_f32_e32 v80, 0x3fb17218, v80
	v_fma_f32 v156, 0, v205, v211
	v_mul_f32_e32 v63, v154, v63
	v_fmamk_f32 v154, v80, 0x3c088888, v186
	v_mul_f32_e32 v78, v79, v78
	v_add_f32_e32 v79, v190, v81
	v_mul_f32_e32 v65, v193, v65
	v_fma_f32 v156, v204, v156, v208
	v_fmaak_f32 v154, v80, v154, 0x3e2aaaab
	v_mul_f32_e32 v79, 0xbfb8aa3b, v79
	v_exp_f32_e32 v213, v65
	v_mul_f32_e32 v65, 0x3fb17218, v65
	v_fma_f32 v156, v42, v156, v43
	v_fma_f32 v154, v80, v154, 0.5
	v_exp_f32_e32 v79, v79
	v_fmamk_f32 v81, v65, 0x3c088888, v186
	v_fma_f32 v216, v40, v156, v41
	v_fma_f32 v156, 0, v207, v210
	v_fma_f32 v154, v80, v154, 1.0
	v_fmaak_f32 v81, v65, v81, 0x3e2aaaab
	v_fma_f32 v156, v206, v156, v209
	v_mul_f32_e32 v154, v80, v154
	v_fma_f32 v155, v64, v64, -1.0
	v_fma_f32 v81, v65, v81, 0.5
	v_fma_f32 v156, v45, v156, v48
	v_cmp_lt_f32_e32 vcc, s76, v80
	ds_read_u16 v0, v0 offset:61360
	v_fma_f32 v81, v65, v81, 1.0
	v_fma_f32 v221, v44, v156, v47
	v_fma_f32 v156, 0, v68, v69
	v_cndmask_b32_e32 v80, v155, v154, vcc
	v_add_f32_e32 v79, 1.0, v79
	v_mul_f32_e32 v81, v65, v81
	v_fma_f32 v154, v213, v213, -1.0
	v_cmp_lt_f32_e32 vcc, s76, v65
	v_fma_f32 v156, v66, v156, v67
	v_rcp_f32_e32 v79, v79
	v_fma_f32 v156, v50, v156, v51
	v_cndmask_b32_e32 v65, v154, v81, vcc
	v_sqrt_f32_e64 v65, -v65
	v_mul_f32_e32 v158, v45, v158
	v_fma_f32 v225, v46, v156, v49
	v_fma_f32 v156, 0, v72, v73
	v_mul_f32_e32 v222, v44, v158
	v_mul_f32_e32 v158, v68, v66
	v_fma_f32 v156, v70, v156, v71
	v_sqrt_f32_e64 v80, -v80
	s_waitcnt lgkmcnt(0)
	v_lshlrev_b32_e32 v0, 16, v0
	v_mul_f32_e32 v158, v50, v158
	v_fma_f32 v156, v54, v156, v55
	v_mul_f32_e32 v0, v79, v0
	v_mul_f32_e32 v226, v46, v158
	v_mul_f32_e32 v158, v72, v70
	v_fma_f32 v229, v52, v156, v53
	v_fma_f32 v156, 0, v76, v77
	v_mul_f32_e32 v214, v65, v0
	v_and_b32_e32 v65, 64, v188
	v_mul_f32_e32 v158, v54, v158
	v_fma_f32 v156, v74, v156, v75
	v_xor_b32_e32 v0, 32, v188
	v_add_u32_e32 v65, 64, v65
	v_mul_f32_e32 v230, v52, v158
	v_mul_f32_e32 v158, v76, v74
	v_fma_f32 v156, v58, v156, v59
	v_mul_f32_e32 v81, v80, v78
	v_cmp_lt_i32_e32 vcc, v0, v65
	v_fma_f32 v65, 0, v198, v199
	v_fma_f32 v154, 0, v202, v203
	v_mul_f32_e32 v158, v58, v158
	v_fma_f32 v233, v56, v156, v57
	v_fma_f32 v156, 0, v213, v214
	v_fma_f32 v65, v196, v65, v197
	v_mul_f32_e32 v78, v198, v196
	v_fma_f32 v154, v200, v154, v201
	v_mul_f32_e32 v155, v202, v200
	v_mul_f32_e32 v234, v56, v158
	v_fma_f32 v156, v64, v156, v81
	v_mul_f32_e32 v158, v213, v64
	v_cndmask_b32_e32 v0, v188, v0, vcc
	v_fma_f32 v65, v147, v65, v195
	v_mul_f32_e32 v78, v147, v78
	v_fma_f32 v154, v38, v154, v39
	v_mul_f32_e32 v155, v38, v155
	v_fma_f32 v156, v62, v156, v63
	v_mul_f32_e32 v159, v62, v158
	v_lshlrev_b32_e32 v0, 2, v0
	v_fma_f32 v65, v34, v65, v35
	v_mul_f32_e32 v78, v34, v78
	v_fma_f32 v154, v36, v154, v37
	v_mul_f32_e32 v155, v36, v155
	v_fma_f32 v158, v60, v156, v61
	v_mul_f32_e32 v156, v60, v159
	ds_bpermute_b32 v79, v0, v78
	ds_bpermute_b32 v80, v0, v65
	ds_bpermute_b32 v212, v0, v155
	ds_bpermute_b32 v215, v0, v154
	ds_bpermute_b32 v218, v0, v217
	ds_bpermute_b32 v219, v0, v216
	ds_bpermute_b32 v223, v0, v222
	ds_bpermute_b32 v224, v0, v221
	ds_bpermute_b32 v227, v0, v226
	ds_bpermute_b32 v228, v0, v225
	ds_bpermute_b32 v231, v0, v230
	ds_bpermute_b32 v232, v0, v229
	ds_bpermute_b32 v235, v0, v234
	ds_bpermute_b32 v236, v0, v233
	ds_bpermute_b32 v220, v0, v156
	ds_bpermute_b32 v237, v0, v158
	s_andn2_b64 vcc, exec, s[4:5]
	s_cbranch_vccnz .LBB0_447
	v_or_b32_e32 v118, 32, v148
	s_load_dwordx2 s[4:5], s[8:9], 0x58
	s_load_dwordx2 s[44:45], s[8:9], 0x68
	v_add_u32_e32 v0, s33, v118
	v_lshlrev_b64 v[114:115], 2, v[0:1]
	v_lshl_or_b32 v0, v118, 6, v149
	s_waitcnt lgkmcnt(0)
	v_lshl_add_u64 v[116:117], s[4:5], 0, v[114:115]
	global_load_dword v192, v[116:117], off
	v_lshl_add_u64 v[116:117], s[44:45], 0, v[114:115]
	global_load_dword v191, v[116:117], off
	v_lshlrev_b64 v[116:117], 1, v[0:1]
	v_lshl_add_u64 v[114:115], s[12:13], 0, v[114:115]
	v_lshl_add_u64 v[138:139], s[14:15], 0, v[116:117]
	v_lshl_add_u64 v[142:143], s[18:19], 0, v[116:117]
	global_load_dword v0, v[114:115], off
	s_nop 0
	global_load_dwordx4 v[114:117], v[138:139], off
	global_load_dwordx4 v[118:121], v[138:139], off offset:32
	global_load_dwordx4 v[122:125], v[138:139], off offset:64
	global_load_dwordx4 v[126:129], v[142:143], off offset:32
	global_load_dwordx4 v[130:133], v[142:143], off offset:64
	global_load_dwordx4 v[134:137], v[142:143], off
	s_nop 0
	global_load_dwordx4 v[138:141], v[138:139], off offset:96
	s_nop 0
	global_load_dwordx4 v[142:145], v[142:143], off offset:96
	s_waitcnt vmcnt(8)
	v_mul_f32_e32 v194, 0x3fb8aa3b, v0
